# workspace pointer kept in s[100:101] for the whole kernel: 81 kernarg scalar loads at phase starts and grid barriers become s_mov
# baseline (speedup 1.0000x reference)
; #define LAS __attribute__((address_space(3)))
; DI unsigned xb_add(unsigned* p, unsigned v) { return __hip_atomic_fetch_add(p, v, __ATOMIC_RELAXED, __HIP_MEMORY_SCOPE_AGENT); }
; DI unsigned xb_xcc_id() { return (unsigned)__builtin_amdgcn_s_getreg((3 << 11) | 20) & 0xFu; }
; #define BARW ((unsigned*)(getargs().ws() + O_BAR))
; __global__ void __launch_bounds__(512, 2) fwd_kernel(Args a_unused) {
;     extern __shared__ __attribute__((aligned(16))) unsigned char shm[];
;     LAS unsigned char* lds = (LAS unsigned char*)shm;
;     const int wv = __builtin_amdgcn_readfirstlane(threadIdx.x >> 6);
;     ...
;     { unsigned* barw0 = BARW; if (threadIdx.x == 0) { BARST[0] = 0u; BARST[1] = 0u; (void)xb_add(&barw0[XB_XCNT(xb_xcc_id())], 1u); } }
_Z10fwd_kernel4Args:
	v_and_b32_e32 v1, 0x3ff, v0
	s_mov_b32 s80, s2
	s_mov_b64 s[82:83], s[0:1]
	s_load_dwordx2 s[100:101], s[0:1], 0xe8
	v_readfirstlane_b32 s48, v1
	s_mov_b64 s[2:3], s[0:1]
	v_cmp_eq_u32_e32 vcc, 0, v1
	s_and_saveexec_b64 s[0:1], vcc
	s_cbranch_execz .LBB0_3
	s_add_i32 s6, 0, 0x22000
	v_mov_b32_e32 v2, 0
	v_mov_b32_e32 v3, s6
	s_add_i32 s6, 0, 0x22004
	s_mov_b64 s[4:5], exec
	ds_write_b32 v3, v2
	v_mov_b32_e32 v3, s6
	ds_write_b32 v3, v2
	v_mbcnt_lo_u32_b32 v2, s4, 0
	v_mbcnt_hi_u32_b32 v2, s5, v2
	v_cmp_eq_u32_e32 vcc, 0, v2
	s_getreg_b32 s6, hwreg(HW_REG_XCC_ID, 0, 4)
	s_and_b64 s[8:9], exec, vcc
	s_mov_b64 exec, s[8:9]
	s_cbranch_execz .LBB0_3
	s_load_dwordx2 s[2:3], s[2:3], 0xe8
	s_lshl_b32 s6, s6, 8
	s_and_b32 s6, s6, 0xf00
	v_mov_b32_e32 v2, 0x1d83000
	s_waitcnt lgkmcnt(0)
	s_add_u32 s2, s2, s6
	s_addc_u32 s3, s3, 0
	s_bcnt1_i32_b64 s4, s[4:5]
	v_mov_b32_e32 v3, s4
	global_atomic_add v2, v3, s[2:3] offset:1024

; #define LAS __attribute__((address_space(3)))
; DI int ltid(int wv) { asm volatile("" : "+s"(wv)); int l = __builtin_amdgcn_mbcnt_hi(~0u, __builtin_amdgcn_mbcnt_lo(~0u, 0u)); asm volatile("" : "+v"(l)); return wv * 64 + l; }
; template <class F> DI void tr_items(const F& f, int Kdst, int Nrows, bf16_t* WT, LAS float* scr, int gw, int NGW, int lane, int& cum) {
;     const int nblk = Nrows / 32, nitems = (Kdst / 64) * nblk;
;     int first = (gw - cum) % NGW; if (first < 0) first += NGW; cum = (cum + nitems) % NGW;
;     for (int item = first; item < nitems; item += NGW) {
;         const int kb = item / nblk, nb = item % nblk, k0 = 64 * kb, n0 = 32 * nb;
; DI void phase_prologue(int wv, const ArgP a, LAS unsigned char* lds, int parts) {
;     unsigned char* ws = a.ws();
;     const int tid = ltid(wv), wave = tid >> 6, lane = tid & 63;
;     LAS float* scr = (LAS float*)(lds + wave * 8448);
;     const int gw = blockIdx.x * 8 + wave, NGW = gridDim.x * 8; int cum = 0;
;     if (parts & 1) {
;     { FW1 f{a.in(3), a.in(2)}; tr_items(f, 1024, 1536, (bf16_t*)(ws + O_W1T), scr, gw, NGW, lane, cum); }
.LBB0_15:
	s_waitcnt lgkmcnt(0)
	v_mbcnt_lo_u32_b32 v0, -1, 0
	s_lshr_b32 s50, s48, 6
	v_mbcnt_hi_u32_b32 v192, -1, v0
	s_mov_b64 s[2:3], s[82:83]
	s_mov_b32 s0, s50
	v_mov_b32_e32 v14, v192
	s_mov_b64 s[12:13], s[100:101]
	s_load_dword s24, s[82:83], 0xf8
	s_lshl_b32 s46, s80, 3
	s_add_u32 s88, s82, 0xf8
	s_addc_u32 s89, s83, 0
	v_lshl_add_u32 v15, s0, 6, v14
	s_waitcnt lgkmcnt(0)
	s_lshl_b32 s14, s24, 3
	s_abs_i32 s15, s14
	v_cvt_f32_u32_e32 v1, s15
	v_ashrrev_i32_e32 v0, 6, v15
	s_movk_i32 s0, 0x2100
	v_mul_lo_u32 v2, v0, s0
	v_rcp_iflag_f32_e32 v3, v1
	v_add_u32_e32 v20, 0, v2
	s_sub_i32 s0, 0, s15
	v_add_u32_e32 v0, s46, v0
	v_mul_f32_e32 v2, 0x4f7ffffe, v3
	v_cvt_u32_f32_e32 v2, v2
	v_sub_u32_e32 v3, 0, v0
	v_max_i32_e32 v3, v0, v3
	v_ashrrev_i32_e32 v1, 31, v0
	v_readfirstlane_b32 s25, v2
	s_mul_i32 s0, s0, s25
	s_mul_hi_u32 s0, s25, s0
	s_add_i32 s25, s25, s0
	v_mul_hi_u32 v2, v3, s25
	v_mul_lo_u32 v2, v2, s15
	v_sub_u32_e32 v2, v3, v2
	v_subrev_u32_e32 v3, s15, v2
	v_cmp_le_u32_e32 vcc, s15, v2
	v_and_b32_e32 v16, 63, v14
	s_movk_i32 s0, 0x300
	v_cndmask_b32_e32 v2, v2, v3, vcc
	v_subrev_u32_e32 v3, s15, v2
	v_cmp_le_u32_e32 vcc, s15, v2
	s_mul_hi_u32 s16, s25, 0x300
	v_and_b32_e32 v18, 31, v14
	v_cndmask_b32_e32 v2, v2, v3, vcc
	v_xor_b32_e32 v2, v2, v1
	v_sub_u32_e32 v2, v2, v1
	v_ashrrev_i32_e32 v3, 31, v2
	v_and_b32_e32 v3, s14, v3
	v_add_u32_e32 v10, v3, v2
	v_cmp_gt_i32_e32 vcc, s0, v10
	v_lshrrev_b32_e32 v17, 5, v16
	v_lshrrev_b32_e32 v19, 3, v16
	v_lshlrev_b32_e32 v21, 3, v16
	s_and_saveexec_b64 s[0:1], vcc
	s_cbranch_execz .LBB0_82
	s_load_dwordx4 s[4:7], s[2:3], 0x10
	v_lshrrev_b32_e32 v13, 3, v16
	v_and_b32_e32 v2, 56, v21
	v_and_b32_e32 v11, 31, v14
	v_lshrrev_b32_e32 v12, 5, v16
	v_mul_u32_u24_e32 v5, 0x84, v2
	v_lshlrev_b32_e32 v2, 1, v2
	v_mov_b32_e32 v3, 0
	v_lshlrev_b32_e32 v6, 2, v13
	v_lshl_add_u32 v4, v11, 2, v20
	v_lshl_add_u64 v[2:3], s[12:13], 0, v[2:3]
	s_mov_b64 s[8:9], 0x3e0b000
	v_add3_u32 v22, v20, v5, v6
	v_mul_u32_u24_e32 v5, 0x84, v12
	v_lshl_add_u64 v[2:3], v[2:3], 0, s[8:9]
	v_lshlrev_b32_e32 v23, 5, v10
	s_lshl_b32 s17, s14, 5
	s_mov_b64 s[8:9], 0
	s_mov_b32 s18, 0x2aaaaaab
	s_movk_i32 s19, 0xfa00
	s_movk_i32 s20, 0x5a0
	s_movk_i32 s21, 0x1680
	v_add_u32_e32 v24, v4, v5
	s_movk_i32 s22, 0x2ff
	s_branch .LBB0_18

; #define LAS __attribute__((address_space(3)))
; DI int ltid(int wv) { asm volatile("" : "+s"(wv)); int l = __builtin_amdgcn_mbcnt_hi(~0u, __builtin_amdgcn_mbcnt_lo(~0u, 0u)); asm volatile("" : "+v"(l)); return wv * 64 + l; }
; DI unsigned xb_ld(unsigned* p) { return __hip_atomic_load(p, __ATOMIC_RELAXED, __HIP_MEMORY_SCOPE_AGENT); }
; DI unsigned xb_add(unsigned* p, unsigned v) { return __hip_atomic_fetch_add(p, v, __ATOMIC_RELAXED, __HIP_MEMORY_SCOPE_AGENT); }
; DI unsigned xb_xcc_id() { return (unsigned)__builtin_amdgcn_s_getreg((3 << 11) | 20) & 0xFu; }
; DI void xcd_barrier_complete(unsigned* bar, unsigned x, unsigned& nloc, unsigned& nx) {
;     const unsigned G = gridDim.x;
;     unsigned sum, cnt, mine, sp = 0u;
;     for (;;) {
;         sum = 0u; cnt = 0u; mine = 0u;
; #pragma unroll
;         for (unsigned j = 0; j < 16; ++j) { const unsigned c = xb_ld(&bar[XB_XCNT(j)]); sum += c; cnt += (c > 0u) ? 1u : 0u; mine = (j == x) ? c : mine; }
;         if (sum == G) break;
; DI void xcd_barrier(int wv, unsigned* bar, volatile LAS unsigned* st) {
;     asm volatile("s_waitcnt vmcnt(0)" ::: "memory");
;     __syncthreads();
;     if (ltid(wv) == 0) {
;         const unsigned x = xb_xcc_id();
;         __builtin_amdgcn_s_waitcnt(0);
;         unsigned nloc = st[0], nx = st[1];
;         if (nloc == 0u) { xcd_barrier_complete(bar, x, nloc, nx); st[0] = nloc; st[1] = nx; }
;         const unsigned old = xb_add(&bar[XB_XSUB(x)], 1u);
.LBB0_316:
	s_or_b64 exec, exec, s[0:1]
	s_mov_b64 s[2:3], s[82:83]
	s_mov_b32 s0, s50
	s_waitcnt vmcnt(0)
	s_waitcnt lgkmcnt(0)
	s_barrier
	s_lshl_b32 s0, s0, 6
	v_mov_b32_e32 v0, v192
	s_sub_i32 s0, 0, s0
	s_nop 0
	v_cmp_eq_u32_e32 vcc, s0, v0
	s_and_saveexec_b64 s[0:1], vcc
	s_xor_b64 s[0:1], exec, s[0:1]
	v_writelane_b32 v240, s50, 0
	s_cbranch_execz .LBB0_369
	s_add_i32 s5, 0, 0x22000
	v_mov_b32_e32 v0, s5
	s_mov_b64 s[2:3], s[100:101]
	s_getreg_b32 s4, hwreg(HW_REG_XCC_ID, 0, 4)
	s_waitcnt vmcnt(0) expcnt(0) lgkmcnt(0)
	ds_read_b32 v2, v0
	s_add_i32 s5, 0, 0x22004
	v_mov_b32_e32 v0, s5
	ds_read_b32 v0, v0
	s_and_b32 s47, s4, 15
	s_waitcnt lgkmcnt(1)
	v_cmp_ne_u32_e32 vcc, 0, v2
	s_cbranch_vccnz .LBB0_332
	s_add_u32 s4, s2, 0x1d83200
	s_addc_u32 s5, s3, 0
	s_add_u32 s6, s2, 0x1d83400
	s_addc_u32 s7, s3, 0
	s_add_u32 s8, s2, 0x1d83500
	s_addc_u32 s9, s3, 0
	s_add_u32 s10, s2, 0x1d83600
	s_addc_u32 s11, s3, 0
	s_add_u32 s12, s2, 0x1d83700
	s_addc_u32 s13, s3, 0
	s_add_u32 s14, s2, 0x1d83800
	s_addc_u32 s15, s3, 0
	s_add_u32 s16, s2, 0x1d83900
	s_addc_u32 s17, s3, 0
	s_add_u32 s18, s2, 0x1d83a00
	s_addc_u32 s19, s3, 0
	s_add_u32 s20, s2, 0x1d83b00
	s_addc_u32 s21, s3, 0
	s_add_u32 s22, s2, 0x1d83c00
	s_addc_u32 s23, s3, 0
	s_add_u32 s24, s2, 0x1d83d00
	s_addc_u32 s25, s3, 0
	s_add_u32 s26, s2, 0x1d83e00
	s_addc_u32 s27, s3, 0
	s_add_u32 s28, s2, 0x1d83f00
	s_addc_u32 s29, s3, 0
	s_add_u32 s30, s2, 0x1d84000
	s_addc_u32 s31, s3, 0
	s_add_u32 s34, s2, 0x1d84100
	s_load_dword s49, s[88:89], 0x0
	s_addc_u32 s35, s3, 0
	s_add_u32 s36, s2, 0x1d84200
	s_addc_u32 s37, s3, 0
	s_add_u32 s38, s2, 0x1d84300
	s_addc_u32 s39, s3, 0
	s_mov_b32 s50, 1
	v_mov_b32_e32 v16, 0
	s_branch .LBB0_320

; DI int ltid(int wv) { asm volatile("" : "+s"(wv)); int l = __builtin_amdgcn_mbcnt_hi(~0u, __builtin_amdgcn_mbcnt_lo(~0u, 0u)); asm volatile("" : "+v"(l)); return wv * 64 + l; }
; DI int lbid() { int t = blockIdx.x; asm volatile("" : "+s"(t)); return t; }
; #define PG8_WAIT_V(n) asm volatile("s_waitcnt vmcnt(" #n ")" ::: "memory")
;     ...
;     const int tid = ltid(wv), wid = __builtin_amdgcn_readfirstlane(tid >> 6), lane = tid & 63, wr = wid >> 2, wc = wid & 3, fr = lane & 15, fq = lane >> 4;
;     const int nt = K / BK;
;     StaticOrder SO; { int c_ = lbid() - rot; if (c_ < 0) c_ += (int)gridDim.x; SO.init(nM, nN, (int)gridDim.x, c_); }
;     unsigned voffA[2], voffB[2];
; #pragma unroll
;     for (int i = 0; i < 2; ++i) { int R, C; stage_rc(tid * 16 + i * 8192, R, C); const int Rb = (R & ~31) + perm32(R & 31);
;         const int Ra = AMAP ? (62 * (R >> 6) + (R & 63) - 2) : R;
;         voffA[i] = (unsigned)((Ra + (AMAP ? 2 : 0)) * lda + C) * 2u; voffB[i] = (unsigned)(Rb * ldb + C) * 2u; }
;     const size_t kstep = (size_t)(BK * 2);
;     const size_t hstepA = (size_t)(AMAP ? 124 : 128) * lda * 2, hstepB = (size_t)HALF * ldb * 2;
;     const size_t tstepA = 2 * hstepA, tstepB = 2 * hstepB;
;     const unsigned ldsw = (unsigned)wid * 1024u;
;     const int aoff = lds_byte(wr * 64 + fr, fq * 8), boff = lds_byte(wc * 32 + fr, fq * 8);
;     ...
;     if (AMAP) A -= 2 * lda;
;     Unit cur, nxt; int ui = 0;
;     if (!SO.next(0, cur)) return;
;     f32x4 acc[2][2][4][2];
; #pragma unroll
;     for (int a = 0; a < 2; ++a)
; #pragma unroll
;         for (int b = 0; b < 2; ++b)
; #pragma unroll
;             for (int m = 0; m < 4; ++m)
; #pragma unroll
;                 for (int n = 0; n < 2; ++n) acc[a][b][m][n] = (f32x4){0.f, 0.f, 0.f, 0.f};
;     bf16x8 At[4][2], B0[2][2], B1[2][2];
;     const char* cA = (const char*)A + (size_t)cur.pm * tstepA + (KOFS ? (cur.pn & 1) * 512 : 0); const char* cB = (const char*)Bt + (size_t)cur.pn * tstepB + (KOFS ? (cur.pn & 1) * 512 : 0);
;     PG8_STAGE(PG8_SB(0, 0), cB, voffB); PG8_STAGE(PG8_SB(0, 1), cB + hstepB, voffB); PG8_STAGE(PG8_SA(0, 0), cA, voffA); PG8_STAGE(PG8_SA(0, 1), cA + hstepA, voffA);
;     if (wr == 1) PG8_BAR;
;     PG8_WAIT_V(2); PG8_BAR;
;     PG8_STAGE(PG8_SB(1, 0), cB + kstep, voffB); PG8_STAGE(PG8_SA(1, 0), cA + kstep, voffA); PG8_STAGE(PG8_SB(1, 1), cB + hstepB + kstep, voffB);
;     PG8_WAIT_V(6); PG8_BAR;
.LBB0_372:
	v_lshlrev_b32_e32 v1, 4, v0
	v_add_u32_e32 v2, 0x2000, v1
	v_ashrrev_i32_e32 v3, 31, v2
	v_lshrrev_b32_e32 v3, 22, v3
	v_add_u32_e32 v3, v2, v3
	v_ashrrev_i32_e32 v9, 10, v3
	v_mul_i32_i24_e32 v3, 0x400, v9
	v_sub_u32_e32 v2, v2, v3
	v_lshrrev_b32_e32 v3, 4, v2
	v_bitop3_b32 v2, v3, v2, 32 bitop3:0x6c
	v_ashrrev_i32_e32 v3, 31, v2
	v_lshrrev_b32_e32 v3, 26, v3
	v_add_u32_e32 v3, v2, v3
	v_lshlrev_b32_e32 v4, 3, v9
	v_ashrrev_i32_e32 v10, 6, v3
	v_and_b32_e32 v4, -16, v4
	v_add_u32_e32 v4, v10, v4
	s_mov_b64 s[8:9], s[100:101]
	s_mov_b64 s[10:11], s[100:101]
	v_and_b32_e32 v5, 3, v10
	s_mov_b32 s4, 0x1fffe0
	v_lshrrev_b32_e32 v6, 2, v4
	v_lshlrev_b32_e32 v7, 1, v4
	v_and_b32_e32 v3, 0xc0, v3
	v_and_or_b32 v5, v4, s4, v5
	v_and_b32_e32 v6, 4, v6
	v_and_b32_e32 v7, 24, v7
	v_sub_u32_e32 v2, v2, v3
	v_mov_b32_e32 v3, 1
	v_or3_b32 v5, v5, v6, v7
	v_lshlrev_b32_e32 v6, 5, v9
	v_ashrrev_i16_sdwa v2, v3, sext(v2) dst_sel:DWORD dst_unused:UNUSED_PAD src0_sel:DWORD src1_sel:BYTE_0
	v_and_b32_e32 v6, 32, v6
	v_bfe_i32 v11, v2, 0, 16
	v_add_lshl_u32 v2, v6, v11, 1
	v_lshl_add_u32 v128, v5, 11, v2
	v_lshl_add_u32 v130, v4, 11, v2
	v_bfe_i32 v2, v0, 27, 1
	v_lshrrev_b32_e32 v2, 22, v2
	v_add_u32_e32 v2, v1, v2
	v_and_b32_e32 v2, 0xfffffc00, v2
	v_sub_u32_e32 v1, v1, v2
	v_lshrrev_b32_e32 v2, 4, v1
	v_ashrrev_i32_e32 v4, 31, v0
	v_bitop3_b32 v1, v2, v1, 32 bitop3:0x6c
	v_lshrrev_b32_e32 v4, 26, v4
	s_ashr_i32 s13, s14, 6
	v_ashrrev_i32_e32 v2, 31, v1
	v_add_u32_e32 v0, v0, v4
	s_ashr_i32 s5, s14, 8
	s_lshl_b32 s34, s13, 10
	s_ashr_i32 s35, s30, 31
	v_lshrrev_b32_e32 v2, 26, v2
	v_ashrrev_i32_e32 v13, 6, v0
	s_waitcnt lgkmcnt(0)
	s_add_u32 s36, s8, 0x1d88000
	v_add_u32_e32 v2, v1, v2
	v_lshlrev_b32_e32 v0, 3, v13
	s_addc_u32 s37, s9, 0
	v_ashrrev_i32_e32 v12, 6, v2
	v_and_b32_e32 v0, -16, v0
	s_add_u32 s38, s10, 0x3e0b000
	v_add_u32_e32 v0, v12, v0
	v_and_b32_e32 v4, 3, v12
	s_addc_u32 s39, s11, 0
	v_and_or_b32 v4, v0, s4, v4
	s_lshr_b32 s4, s35, 29
	s_add_i32 s4, s30, s4
	s_ashr_i32 s6, s4, 3
	s_and_b32 s4, s4, -8
	s_sub_i32 s4, s30, s4
	s_cmp_lt_i32 s4, 0
	s_cselect_b32 s7, 49, 48
	s_mul_i32 s4, s7, s4
	s_add_i32 s4, s4, s6
	s_mul_hi_i32 s6, s4, 0x2aaaaaab
	s_lshr_b32 s7, s6, 31
	s_ashr_i32 s6, s6, 3
	s_add_i32 s6, s6, s7
	s_lshl_b32 s7, s6, 3
	s_mul_i32 s6, s6, 48
	s_sub_i32 s6, s4, s6
	s_bfe_i32 s4, s6, 0x80000
	s_bfe_u32 s4, s4, 0x3000c
	s_add_i32 s8, s6, s4
	s_bfe_i32 s4, s8, 0x80000
	s_and_b32 s8, s8, 0xf8
	s_sub_i32 s6, s6, s8
	s_sext_i32_i16 s4, s4
	s_sext_i32_i8 s6, s6
	v_lshrrev_b32_e32 v5, 2, v0
	v_lshlrev_b32_e32 v6, 1, v0
	v_and_b32_e32 v2, 0xc0, v2
	s_lshr_b32 s4, s4, 3
	s_add_i32 s6, s7, s6
	v_and_b32_e32 v5, 4, v5
	v_and_b32_e32 v6, 24, v6
	v_sub_u32_e32 v1, v1, v2
	s_ashr_i32 s7, s6, 31
	s_bfe_i64 s[10:11], s[4:5], 0x100000
	v_or3_b32 v4, v4, v5, v6
	v_lshlrev_b32_e32 v5, 5, v13
	v_ashrrev_i16_sdwa v1, v3, sext(v1) dst_sel:DWORD dst_unused:UNUSED_PAD src0_sel:DWORD src1_sel:BYTE_0
	s_lshl_b64 s[8:9], s[6:7], 19
	s_lshl_b64 s[10:11], s[10:11], 19
	v_and_b32_e32 v5, 32, v5
	v_bfe_i32 v14, v1, 0, 16
	s_add_u32 s26, s38, s10
	v_add_lshl_u32 v1, v5, v14, 1
	s_addc_u32 s27, s39, s11
	s_add_i32 s40, s34, 0
	v_lshl_add_u32 v132, v4, 11, v1
	s_add_i32 m0, s40, 0x10000
	v_lshl_add_u32 v134, v0, 11, v1
	global_load_lds_dwordx4 v132, s[26:27]
	s_add_i32 m0, s40, 0x12000
	s_add_u32 s10, s26, 0x40000
	global_load_lds_dwordx4 v128, s[26:27]
	s_addc_u32 s11, s27, 0
	s_add_i32 m0, s40, 0x14000
	v_mov_b32_e32 v133, 0
	global_load_lds_dwordx4 v132, s[10:11]
	s_add_i32 m0, s40, 0x16000
	s_add_u32 s24, s36, s8
	s_addc_u32 s25, s37, s9
	s_add_i32 s41, s40, 0x2000
	global_load_lds_dwordx4 v128, s[10:11]
	s_mov_b32 m0, s40
	s_add_u32 s8, s24, 0x40000
	global_load_lds_dwordx4 v134, s[24:25]
	s_mov_b32 m0, s41
	s_addc_u32 s9, s25, 0
	s_add_i32 s42, s40, 0x4000
	global_load_lds_dwordx4 v130, s[24:25]
	s_mov_b32 m0, s42
	s_add_i32 s43, s40, 0x6000
	global_load_lds_dwordx4 v134, s[8:9]
	s_mov_b32 m0, s43
	v_mov_b32_e32 v129, v133
	global_load_lds_dwordx4 v130, s[8:9]
	s_mov_b64 s[10:11], s[100:101]
	s_mov_b64 s[8:9], s[100:101]
	v_mov_b32_e32 v135, v133
	v_mov_b32_e32 v131, v133
	s_cmp_eq_u32 s5, 1
	s_mov_b32 s44, 0
	v_lshl_add_u64 v[6:7], s[26:27], 0, v[132:133]
	v_lshl_add_u64 v[4:5], s[26:27], 0, v[128:129]
	v_lshl_add_u64 v[0:1], s[24:25], 0, v[134:135]
	s_cselect_b64 s[0:1], -1, 0
	s_cmp_lg_u32 s5, 1
	v_lshl_add_u64 v[2:3], s[24:25], 0, v[130:131]
	s_cbranch_scc1 .LBB0_374
	s_barrier

; #define LAS __attribute__((address_space(3)))
; DI int ltid(int wv) { asm volatile("" : "+s"(wv)); int l = __builtin_amdgcn_mbcnt_hi(~0u, __builtin_amdgcn_mbcnt_lo(~0u, 0u)); asm volatile("" : "+v"(l)); return wv * 64 + l; }
; DI unsigned xb_ld(unsigned* p) { return __hip_atomic_load(p, __ATOMIC_RELAXED, __HIP_MEMORY_SCOPE_AGENT); }
; DI unsigned xb_add(unsigned* p, unsigned v) { return __hip_atomic_fetch_add(p, v, __ATOMIC_RELAXED, __HIP_MEMORY_SCOPE_AGENT); }
; DI unsigned xb_xcc_id() { return (unsigned)__builtin_amdgcn_s_getreg((3 << 11) | 20) & 0xFu; }
; DI void xcd_barrier_complete(unsigned* bar, unsigned x, unsigned& nloc, unsigned& nx) {
;     const unsigned G = gridDim.x;
;     unsigned sum, cnt, mine, sp = 0u;
;     for (;;) {
;         sum = 0u; cnt = 0u; mine = 0u;
; #pragma unroll
;         for (unsigned j = 0; j < 16; ++j) { const unsigned c = xb_ld(&bar[XB_XCNT(j)]); sum += c; cnt += (c > 0u) ? 1u : 0u; mine = (j == x) ? c : mine; }
;         if (sum == G) break;
; DI void xcd_barrier(int wv, unsigned* bar, volatile LAS unsigned* st) {
;     asm volatile("s_waitcnt vmcnt(0)" ::: "memory");
;     __syncthreads();
;     if (ltid(wv) == 0) {
;         const unsigned x = xb_xcc_id();
;         __builtin_amdgcn_s_waitcnt(0);
;         unsigned nloc = st[0], nx = st[1];
;         if (nloc == 0u) { xcd_barrier_complete(bar, x, nloc, nx); st[0] = nloc; st[1] = nx; }
;         const unsigned old = xb_add(&bar[XB_XSUB(x)], 1u);
.LBB0_388:
	s_mov_b64 s[2:3], s[82:83]
	s_mov_b32 s0, s50
	s_waitcnt vmcnt(0)
	s_waitcnt lgkmcnt(0)
	s_barrier
	s_lshl_b32 s0, s0, 6
	v_mov_b32_e32 v0, v192
	s_sub_i32 s0, 0, s0
	s_nop 0
	v_cmp_eq_u32_e32 vcc, s0, v0
	s_and_saveexec_b64 s[0:1], vcc
	s_xor_b64 s[0:1], exec, s[0:1]
	s_cbranch_execz .LBB0_441
	s_add_i32 s5, 0, 0x22000
	v_mov_b32_e32 v0, s5
	s_mov_b64 s[2:3], s[100:101]
	s_getreg_b32 s4, hwreg(HW_REG_XCC_ID, 0, 4)
	s_waitcnt vmcnt(0) expcnt(0) lgkmcnt(0)
	ds_read_b32 v2, v0
	s_add_i32 s5, 0, 0x22004
	v_mov_b32_e32 v0, s5
	ds_read_b32 v0, v0
	s_and_b32 s47, s4, 15
	s_waitcnt lgkmcnt(1)
	v_cmp_ne_u32_e32 vcc, 0, v2
	s_cbranch_vccnz .LBB0_404
	s_add_u32 s4, s2, 0x1d83200
	s_addc_u32 s5, s3, 0
	s_add_u32 s6, s2, 0x1d83400
	s_addc_u32 s7, s3, 0
	s_add_u32 s8, s2, 0x1d83500
	s_addc_u32 s9, s3, 0
	s_add_u32 s10, s2, 0x1d83600
	s_addc_u32 s11, s3, 0
	s_add_u32 s12, s2, 0x1d83700
	s_addc_u32 s13, s3, 0
	s_add_u32 s14, s2, 0x1d83800
	s_addc_u32 s15, s3, 0
	s_add_u32 s16, s2, 0x1d83900
	s_addc_u32 s17, s3, 0
	s_add_u32 s18, s2, 0x1d83a00
	s_addc_u32 s19, s3, 0
	s_add_u32 s20, s2, 0x1d83b00
	s_addc_u32 s21, s3, 0
	s_add_u32 s22, s2, 0x1d83c00
	s_addc_u32 s23, s3, 0
	s_add_u32 s24, s2, 0x1d83d00
	s_addc_u32 s25, s3, 0
	s_add_u32 s26, s2, 0x1d83e00
	s_addc_u32 s27, s3, 0
	s_add_u32 s28, s2, 0x1d83f00
	s_addc_u32 s29, s3, 0
	s_add_u32 s30, s2, 0x1d84000
	s_addc_u32 s31, s3, 0
	s_add_u32 s34, s2, 0x1d84100
	s_load_dword s49, s[88:89], 0x0
	s_addc_u32 s35, s3, 0
	s_add_u32 s36, s2, 0x1d84200
	s_addc_u32 s37, s3, 0
	s_add_u32 s38, s2, 0x1d84300
	s_addc_u32 s39, s3, 0
	s_mov_b32 s50, 1
	v_mov_b32_e32 v16, 0
	s_branch .LBB0_392

; DI unsigned pk2(float lo, float hi) { f32x2 v = {lo, hi}; bf16x2_t b = __builtin_convertvector(v, bf16x2_t); return __builtin_bit_cast(unsigned, b); }
; DI int ltid(int wv) { asm volatile("" : "+s"(wv)); int l = __builtin_amdgcn_mbcnt_hi(~0u, __builtin_amdgcn_mbcnt_lo(~0u, 0u)); asm volatile("" : "+v"(l)); return wv * 64 + l; }
; DI float bflo(unsigned u) { return __uint_as_float(u << 16); }
; DI float bfhi(unsigned u) { return __uint_as_float(u & 0xffff0000u); }
; DI void phase_l0_prep(int wv, const ArgP a) {
;     unsigned char* ws = a.ws();
;     const bf16_t* Z = (const bf16_t*)(ws + O_Z); bf16_t* XC = (bf16_t*)(ws + O_XC); bf16_t* KB = (bf16_t*)(ws + O_KB);
;     float* rsq = (float*)(ws + O_RSQ); float* rskv = (float*)(ws + O_RSKV); const float* cst = (const float*)(ws + O_CSTAB);
;     const float* cw = a.in(4); const float* cb = a.in(5);
;     const int tid = ltid(wv), wave = tid >> 6, lane = tid & 63;
; #pragma unroll 2
;     for (int e = blockIdx.x * 512 + tid; e < S * 64; e += gridDim.x * 512) { const int t = e >> 6, c0 = (e & 63) * 8;
;         float acc[8];
; #pragma unroll
;         for (int j = 0; j < 8; ++j) acc[j] = cb[c0 + j];
; #pragma unroll
;         for (int k = 0; k < 4; ++k) { const int tt = t - 3 + k; if (tt < 0) continue;
;             const u32x4 v = *(const u32x4*)(Z + (size_t)tt * 1536 + c0);
;             const f32x4 w0 = *(const f32x4*)(cw + k * 512 + c0), w1 = *(const f32x4*)(cw + k * 512 + c0 + 4);
;             acc[0] += w0[0] * bflo(v.x); acc[1] += w0[1] * bfhi(v.x); acc[2] += w0[2] * bflo(v.y); acc[3] += w0[3] * bfhi(v.y);
;             acc[4] += w1[0] * bflo(v.z); acc[5] += w1[1] * bfhi(v.z); acc[6] += w1[2] * bflo(v.w); acc[7] += w1[3] * bfhi(v.w); }
;         u32x4 o; o.x = pk2(acc[0], acc[1]); o.y = pk2(acc[2], acc[3]); o.z = pk2(acc[4], acc[5]); o.w = pk2(acc[6], acc[7]);
;         *(u32x4*)(XC + (size_t)t * 512 + c0) = o; }
.LBB0_441:
	s_or_b64 exec, exec, s[0:1]
	s_mov_b64 s[12:13], s[82:83]
	s_waitcnt lgkmcnt(0)
	s_barrier
	s_mov_b64 s[0:1], s[100:101]
	s_mov_b32 s4, s50
	v_mov_b32_e32 v18, v192
	s_waitcnt lgkmcnt(0)
	s_add_u32 s2, s0, 0x556b000
	v_lshl_add_u32 v19, s4, 6, v18
	v_add_u32_e32 v21, s33, v19
	s_mov_b32 s22, 0x100000
	s_addc_u32 s3, s1, 0
	v_cmp_gt_i32_e32 vcc, s22, v21
	s_and_saveexec_b64 s[8:9], vcc
	s_cbranch_execz .LBB0_462
	s_load_dword s14, s[88:89], 0x0
	s_load_dwordx4 s[4:7], s[12:13], 0x20
	s_add_u32 s10, s0, 0x856b000
	s_addc_u32 s11, s1, 0
	v_lshlrev_b32_e32 v20, 3, v21
	v_and_b32_e32 v10, 0x1f8, v20
	v_lshlrev_b32_e32 v8, 2, v10
	v_lshlrev_b32_e32 v10, 1, v10
	s_movk_i32 s25, 0xc00
	s_waitcnt lgkmcnt(0)
	s_add_u32 s12, s4, 0x1000
	s_addc_u32 s13, s5, 0
	s_lshl_b32 s23, s14, 9
	global_load_dwordx4 v[40:43], v8, s[4:5]
	global_load_dwordx4 v[44:47], v8, s[4:5] offset:16
	global_load_dwordx4 v[48:51], v8, s[4:5] offset:2048
	global_load_dwordx4 v[52:55], v8, s[4:5] offset:2064
	global_load_dwordx4 v[56:59], v8, s[12:13]
	global_load_dwordx4 v[60:63], v8, s[12:13] offset:16
	global_load_dwordx4 v[64:67], v8, s[12:13] offset:2048
	global_load_dwordx4 v[68:71], v8, s[12:13] offset:2064
	global_load_dwordx4 v[72:75], v8, s[6:7]
	global_load_dwordx4 v[76:79], v8, s[6:7] offset:16

; #define LAS __attribute__((address_space(3)))
; DI int ltid(int wv) { asm volatile("" : "+s"(wv)); int l = __builtin_amdgcn_mbcnt_hi(~0u, __builtin_amdgcn_mbcnt_lo(~0u, 0u)); asm volatile("" : "+v"(l)); return wv * 64 + l; }
; DI unsigned xb_ld(unsigned* p) { return __hip_atomic_load(p, __ATOMIC_RELAXED, __HIP_MEMORY_SCOPE_AGENT); }
; DI unsigned xb_add(unsigned* p, unsigned v) { return __hip_atomic_fetch_add(p, v, __ATOMIC_RELAXED, __HIP_MEMORY_SCOPE_AGENT); }
; DI unsigned xb_xcc_id() { return (unsigned)__builtin_amdgcn_s_getreg((3 << 11) | 20) & 0xFu; }
; DI void xcd_barrier_complete(unsigned* bar, unsigned x, unsigned& nloc, unsigned& nx) {
;     const unsigned G = gridDim.x;
;     unsigned sum, cnt, mine, sp = 0u;
;     for (;;) {
;         sum = 0u; cnt = 0u; mine = 0u;
; #pragma unroll
;         for (unsigned j = 0; j < 16; ++j) { const unsigned c = xb_ld(&bar[XB_XCNT(j)]); sum += c; cnt += (c > 0u) ? 1u : 0u; mine = (j == x) ? c : mine; }
;         if (sum == G) break;
; DI void xcd_barrier(int wv, unsigned* bar, volatile LAS unsigned* st) {
;     asm volatile("s_waitcnt vmcnt(0)" ::: "memory");
;     __syncthreads();
;     if (ltid(wv) == 0) {
;         const unsigned x = xb_xcc_id();
;         __builtin_amdgcn_s_waitcnt(0);
;         unsigned nloc = st[0], nx = st[1];
;         if (nloc == 0u) { xcd_barrier_complete(bar, x, nloc, nx); st[0] = nloc; st[1] = nx; }
;         const unsigned old = xb_add(&bar[XB_XSUB(x)], 1u);
.LBB0_469:
	s_or_b64 exec, exec, s[10:11]
	s_mov_b64 s[2:3], s[82:83]
	s_mov_b32 s0, s50
	s_waitcnt vmcnt(0)
	s_waitcnt lgkmcnt(0)
	s_barrier
	s_lshl_b32 s0, s0, 6
	v_mov_b32_e32 v0, v192
	s_sub_i32 s0, 0, s0
	s_nop 0
	v_cmp_eq_u32_e32 vcc, s0, v0
	s_and_saveexec_b64 s[0:1], vcc
	s_xor_b64 s[0:1], exec, s[0:1]
	s_cbranch_execz .LBB0_522
	s_add_i32 s5, 0, 0x22000
	v_mov_b32_e32 v0, s5
	s_mov_b64 s[2:3], s[100:101]
	s_getreg_b32 s4, hwreg(HW_REG_XCC_ID, 0, 4)
	s_waitcnt vmcnt(0) expcnt(0) lgkmcnt(0)
	ds_read_b32 v2, v0
	s_add_i32 s5, 0, 0x22004
	v_mov_b32_e32 v0, s5
	ds_read_b32 v0, v0
	s_and_b32 s33, s4, 15
	s_waitcnt lgkmcnt(1)
	v_cmp_ne_u32_e32 vcc, 0, v2
	s_cbranch_vccnz .LBB0_485
	s_add_u32 s4, s2, 0x1d83200
	s_addc_u32 s5, s3, 0
	s_add_u32 s6, s2, 0x1d83400
	s_addc_u32 s7, s3, 0
	s_add_u32 s8, s2, 0x1d83500
	s_addc_u32 s9, s3, 0
	s_add_u32 s10, s2, 0x1d83600
	s_addc_u32 s11, s3, 0
	s_add_u32 s12, s2, 0x1d83700
	s_addc_u32 s13, s3, 0
	s_add_u32 s14, s2, 0x1d83800
	s_addc_u32 s15, s3, 0
	s_add_u32 s16, s2, 0x1d83900
	s_addc_u32 s17, s3, 0
	s_add_u32 s18, s2, 0x1d83a00
	s_addc_u32 s19, s3, 0
	s_add_u32 s20, s2, 0x1d83b00
	s_addc_u32 s21, s3, 0
	s_add_u32 s22, s2, 0x1d83c00
	s_addc_u32 s23, s3, 0
	s_add_u32 s24, s2, 0x1d83d00
	s_addc_u32 s25, s3, 0
	s_add_u32 s26, s2, 0x1d83e00
	s_addc_u32 s27, s3, 0
	s_add_u32 s28, s2, 0x1d83f00
	s_addc_u32 s29, s3, 0
	s_add_u32 s30, s2, 0x1d84000
	s_addc_u32 s31, s3, 0
	s_add_u32 s34, s2, 0x1d84100
	s_load_dword s46, s[88:89], 0x0
	s_addc_u32 s35, s3, 0
	s_add_u32 s36, s2, 0x1d84200
	s_addc_u32 s37, s3, 0
	s_add_u32 s38, s2, 0x1d84300
	s_addc_u32 s39, s3, 0
	s_mov_b32 s47, 1
	v_mov_b32_e32 v16, 0
	s_branch .LBB0_473

; #define WSB (getargs().ws())
;     DI bool next(int i, Unit& u) const {
;         const long L = (long)i * G + c; if (L >= nwg) return false;
;         int wgid = (int)L; { const int q = nwg / NXCD, r = nwg % NXCD, xcd = wgid % NXCD, off = wgid / NXCD; wgid = (xcd < r ? xcd * (q + 1) : r * (q + 1) + (xcd - r) * q) + off; }
;         const int nig = WGM * nN, gid = wgid / nig, fm = gid * WGM, gsz = (nM - fm) < WGM ? (nM - fm) : WGM;
;         u.pm = fm + ((wgid % nig) % gsz); u.pn = (wgid % nig) / gsz; return true;
; __global__ void __launch_bounds__(512, 2) fwd_kernel(Args a_unused) {
;     ...
;     { EpiRowBf16<0> E{(bf16_t*)(WSB + O_RI), 1024, nullptr};
;       pg8::gemm_phase<false, EpiRowBf16<0>, true>(wv, lds, (const bf16_t*)(WSB + O_XC), 512, (const bf16_t*)(WSB + O_WRIT), 512, 256, 64, 4, E); }
.LBB0_525:
	s_ashr_i32 s39, s33, 31
	s_mov_b64 s[4:5], s[100:101]
	s_mov_b64 s[0:1], s[100:101]
	s_lshr_b32 s6, s39, 29
	s_add_i32 s12, s33, s6
	s_and_b32 s6, s12, -8
	s_sub_i32 s8, s33, s6
	s_cmp_gt_i32 s8, -1
	s_cbranch_scc0 .LBB0_527
	s_lshl_b32 s9, s8, 5
	s_mov_b64 s[2:3], s[100:101]
	s_ashr_i32 s7, s12, 3
	s_cbranch_execz .LBB0_528
	s_branch .LBB0_529
.LBB0_527:
	s_mov_b64 s[2:3], s[100:101]
	s_ashr_i32 s7, s12, 3

; DI int ltid(int wv) { asm volatile("" : "+s"(wv)); int l = __builtin_amdgcn_mbcnt_hi(~0u, __builtin_amdgcn_mbcnt_lo(~0u, 0u)); asm volatile("" : "+v"(l)); return wv * 64 + l; }
; DI int lbid() { int t = blockIdx.x; asm volatile("" : "+s"(t)); return t; }
; #define PG8_WAIT_V(n) asm volatile("s_waitcnt vmcnt(" #n ")" ::: "memory")
;     ...
;     const int tid = ltid(wv), wid = __builtin_amdgcn_readfirstlane(tid >> 6), lane = tid & 63, wr = wid >> 2, wc = wid & 3, fr = lane & 15, fq = lane >> 4;
;     const int nt = K / BK;
;     StaticOrder SO; { int c_ = lbid() - rot; if (c_ < 0) c_ += (int)gridDim.x; SO.init(nM, nN, (int)gridDim.x, c_); }
;     unsigned voffA[2], voffB[2];
; #pragma unroll
;     for (int i = 0; i < 2; ++i) { int R, C; stage_rc(tid * 16 + i * 8192, R, C); const int Rb = (R & ~31) + perm32(R & 31);
;         const int Ra = AMAP ? (62 * (R >> 6) + (R & 63) - 2) : R;
;         voffA[i] = (unsigned)((Ra + (AMAP ? 2 : 0)) * lda + C) * 2u; voffB[i] = (unsigned)(Rb * ldb + C) * 2u; }
;     const size_t kstep = (size_t)(BK * 2);
;     const size_t hstepA = (size_t)(AMAP ? 124 : 128) * lda * 2, hstepB = (size_t)HALF * ldb * 2;
;     const size_t tstepA = 2 * hstepA, tstepB = 2 * hstepB;
;     const unsigned ldsw = (unsigned)wid * 1024u;
;     const int aoff = lds_byte(wr * 64 + fr, fq * 8), boff = lds_byte(wc * 32 + fr, fq * 8);
;     ...
;     if (AMAP) A -= 2 * lda;
;     Unit cur, nxt; int ui = 0;
;     if (!SO.next(0, cur)) return;
;     f32x4 acc[2][2][4][2];
; #pragma unroll
;     for (int a = 0; a < 2; ++a)
; #pragma unroll
;         for (int b = 0; b < 2; ++b)
; #pragma unroll
;             for (int m = 0; m < 4; ++m)
; #pragma unroll
;                 for (int n = 0; n < 2; ++n) acc[a][b][m][n] = (f32x4){0.f, 0.f, 0.f, 0.f};
;     bf16x8 At[4][2], B0[2][2], B1[2][2];
;     const char* cA = (const char*)A + (size_t)cur.pm * tstepA + (KOFS ? (cur.pn & 1) * 512 : 0); const char* cB = (const char*)Bt + (size_t)cur.pn * tstepB + (KOFS ? (cur.pn & 1) * 512 : 0);
;     PG8_STAGE(PG8_SB(0, 0), cB, voffB); PG8_STAGE(PG8_SB(0, 1), cB + hstepB, voffB); PG8_STAGE(PG8_SA(0, 0), cA, voffA); PG8_STAGE(PG8_SA(0, 1), cA + hstepA, voffA);
;     if (wr == 1) PG8_BAR;
;     PG8_WAIT_V(2); PG8_BAR;
;     PG8_STAGE(PG8_SB(1, 0), cB + kstep, voffB); PG8_STAGE(PG8_SA(1, 0), cA + kstep, voffA); PG8_STAGE(PG8_SB(1, 1), cB + hstepB + kstep, voffB);
;     PG8_WAIT_V(6); PG8_BAR;
.LBB0_553:
	s_andn2_b64 vcc, exec, s[10:11]
	s_cbranch_vccnz .LBB0_604
	v_ashrrev_i32_e32 v2, 31, v0
	v_lshrrev_b32_e32 v2, 26, v2
	v_lshlrev_b32_e32 v1, 4, v0
	v_add_u32_e32 v2, v0, v2
	v_bfe_i32 v0, v0, 27, 1
	v_lshrrev_b32_e32 v0, 22, v0
	v_add_u32_e32 v0, v1, v0
	v_and_b32_e32 v0, 0xfffffc00, v0
	v_sub_u32_e32 v0, v1, v0
	v_ashrrev_i32_e32 v9, 6, v2
	v_lshrrev_b32_e32 v2, 4, v0
	v_bitop3_b32 v0, v2, v0, 32 bitop3:0x6c
	v_ashrrev_i32_e32 v3, 31, v0
	v_lshrrev_b32_e32 v3, 26, v3
	v_add_u32_e32 v3, v0, v3
	v_lshlrev_b32_e32 v2, 3, v9
	v_ashrrev_i32_e32 v10, 6, v3
	v_and_b32_e32 v3, 0xc0, v3
	v_and_b32_e32 v2, -16, v2
	v_sub_u32_e32 v0, v0, v3
	v_mov_b32_e32 v3, 1
	v_add_u32_e32 v2, v10, v2
	v_lshlrev_b32_e32 v4, 5, v9
	v_ashrrev_i16_sdwa v0, v3, sext(v0) dst_sel:DWORD dst_unused:UNUSED_PAD src0_sel:DWORD src1_sel:BYTE_0
	s_mov_b64 s[10:11], s[100:101]
	s_mov_b64 s[20:21], s[100:101]
	v_and_b32_e32 v11, 32, v4
	v_bfe_i32 v12, v0, 0, 16
	v_lshlrev_b32_e32 v4, 1, v2
	v_lshrrev_b32_e32 v5, 2, v2
	v_and_b32_e32 v6, 3, v10
	s_mov_b32 s6, 0x7fffe0
	s_movk_i32 s18, 0x600
	v_add_u32_e32 v0, v11, v12
	v_and_b32_e32 v4, 24, v4
	v_and_b32_e32 v5, 4, v5
	v_and_or_b32 v6, v2, s6, v6
	v_mul_lo_u32 v2, v2, s18
	v_or3_b32 v4, v6, v5, v4
	v_add_lshl_u32 v128, v0, v2, 1
	v_lshlrev_b32_e32 v0, 1, v0
	v_lshl_add_u32 v130, v4, 9, v0
	v_add_u32_e32 v0, 0x2000, v1
	v_ashrrev_i32_e32 v1, 31, v0
	v_lshrrev_b32_e32 v1, 22, v1
	v_add_u32_e32 v1, v0, v1
	v_ashrrev_i32_e32 v13, 10, v1
	v_mul_i32_i24_e32 v1, 0x400, v13
	v_sub_u32_e32 v0, v0, v1
	v_lshrrev_b32_e32 v1, 4, v0
	s_ashr_i32 s12, s16, 6
	v_bitop3_b32 v0, v1, v0, 32 bitop3:0x6c
	s_ashr_i32 s15, s16, 8
	v_ashrrev_i32_e32 v2, 31, v0
	s_lshl_b32 s36, s12, 10
	v_lshrrev_b32_e32 v2, 26, v2
	s_waitcnt lgkmcnt(0)
	s_add_u32 s37, s10, 0x556b800
	v_lshlrev_b32_e32 v1, 3, v13
	v_add_u32_e32 v2, v0, v2
	s_addc_u32 s38, s11, 0
	v_and_b32_e32 v1, -16, v1
	v_ashrrev_i32_e32 v14, 6, v2
	v_lshlrev_b32_e32 v4, 5, v13
	s_add_u32 s39, s20, 0x410b000
	v_add_u32_e32 v1, v14, v1
	v_and_b32_e32 v15, 32, v4
	v_and_b32_e32 v2, 0xc0, v2
	v_and_b32_e32 v4, 3, v14
	s_addc_u32 s40, s21, 0
	s_ashr_i32 s25, s24, 31
	v_sub_u32_e32 v0, v0, v2
	v_and_or_b32 v4, v1, s6, v4
	s_lshl_b64 s[6:7], s[24:25], 17
	v_ashrrev_i16_sdwa v0, v3, sext(v0) dst_sel:DWORD dst_unused:UNUSED_PAD src0_sel:DWORD src1_sel:BYTE_0
	s_add_u32 s28, s39, s6
	v_bfe_i32 v16, v0, 0, 16
	v_lshlrev_b32_e32 v2, 1, v1
	v_lshrrev_b32_e32 v3, 2, v1
	s_addc_u32 s29, s40, s7
	s_add_i32 s41, s36, 0
	v_add_u32_e32 v0, v15, v16
	v_and_b32_e32 v2, 24, v2
	v_and_b32_e32 v3, 4, v3
	v_mul_lo_u32 v1, v1, s18
	s_add_i32 m0, s41, 0x10000
	v_or3_b32 v2, v4, v3, v2
	v_add_lshl_u32 v132, v0, v1, 1
	v_lshlrev_b32_e32 v0, 1, v0
	global_load_lds_dwordx4 v130, s[28:29]
	s_add_i32 m0, s41, 0x12000
	v_lshl_add_u32 v134, v2, 9, v0
	s_add_u32 s6, s28, 0x10000
	global_load_lds_dwordx4 v134, s[28:29]
	s_addc_u32 s7, s29, 0
	s_add_i32 m0, s41, 0x14000
	s_mul_i32 s9, s58, 0xc0000
	global_load_lds_dwordx4 v130, s[6:7]
	s_add_i32 m0, s41, 0x16000
	s_mul_hi_i32 s8, s58, 0xc0000
	s_add_u32 s26, s37, s9
	s_addc_u32 s27, s38, s8
	s_add_i32 s42, s41, 0x2000
	global_load_lds_dwordx4 v134, s[6:7]
	s_mov_b32 m0, s41
	s_add_u32 s6, s26, 0x60000
	global_load_lds_dwordx4 v128, s[26:27]
	s_mov_b32 m0, s42
	s_addc_u32 s7, s27, 0
	s_add_i32 s43, s41, 0x4000
	global_load_lds_dwordx4 v132, s[26:27]
	s_mov_b32 m0, s43
	s_add_i32 s44, s41, 0x6000
	global_load_lds_dwordx4 v128, s[6:7]
	s_mov_b32 m0, s44
	v_mov_b32_e32 v137, 0
	global_load_lds_dwordx4 v132, s[6:7]
	s_mov_b64 s[10:11], s[100:101]
	s_mov_b64 s[8:9], s[100:101]
	s_mov_b64 s[6:7], s[100:101]
	v_mov_b32_e32 v131, v137
	v_mov_b32_e32 v135, v137
	v_mov_b32_e32 v129, v137
	v_mov_b32_e32 v133, v137
	s_cmp_eq_u32 s15, 1
	s_movk_i32 s45, 0xc0
	s_mov_b32 s46, 0
	v_lshl_add_u64 v[6:7], s[28:29], 0, v[130:131]
	v_lshl_add_u64 v[4:5], s[28:29], 0, v[134:135]
	v_lshl_add_u64 v[2:3], s[26:27], 0, v[128:129]
	v_lshl_add_u64 v[0:1], s[26:27], 0, v[132:133]
	s_cselect_b64 s[0:1], -1, 0
	s_cmp_lg_u32 s15, 1
	s_movk_i32 s4, 0x6000
	s_cbranch_scc1 .LBB0_556
	s_barrier

; #define WSB (getargs().ws())
;     DI bool next(int i, Unit& u) const {
;         const long L = (long)i * G + c; if (L >= nwg) return false;
;         int wgid = (int)L; { const int q = nwg / NXCD, r = nwg % NXCD, xcd = wgid % NXCD, off = wgid / NXCD; wgid = (xcd < r ? xcd * (q + 1) : r * (q + 1) + (xcd - r) * q) + off; }
;         const int nig = WGM * nN, gid = wgid / nig, fm = gid * WGM, gsz = (nM - fm) < WGM ? (nM - fm) : WGM;
;         u.pm = fm + ((wgid % nig) % gsz); u.pn = (wgid % nig) / gsz; return true;
; __global__ void __launch_bounds__(512, 2) fwd_kernel(Args a_unused) {
;     ...
;     { EpiK E{(bf16_t*)(WSB + O_KB), (const float*)(WSB + O_RSKV)};
;       pg8::gemm_phase<false>(wv, lds, (const bf16_t*)(WSB + O_Z) + 1280, 1536, (const bf16_t*)(WSB + O_WKT), 256, 256, 64, 2, E, 192); }
.LBB0_606:
	s_cmpk_gt_i32 s27, 0x7f
	s_cbranch_scc1 .LBB0_633
	s_ashr_i32 s28, s27, 31
	s_mov_b64 s[6:7], s[100:101]
	s_mov_b64 s[4:5], s[100:101]
	s_lshr_b32 s8, s28, 29
	s_add_i32 s14, s27, s8
	s_and_b32 s8, s14, -8
	s_sub_i32 s10, s27, s8
	s_cmp_gt_i32 s10, -1
	s_cbranch_scc0 .LBB0_609
	s_lshl_b32 s11, s10, 4
	s_mov_b64 s[2:3], s[100:101]
	s_ashr_i32 s9, s14, 3
	s_cbranch_execz .LBB0_610
	s_branch .LBB0_611
.LBB0_609:
	s_mov_b64 s[2:3], s[100:101]
	s_ashr_i32 s9, s14, 3

; DI int ltid(int wv) { asm volatile("" : "+s"(wv)); int l = __builtin_amdgcn_mbcnt_hi(~0u, __builtin_amdgcn_mbcnt_lo(~0u, 0u)); asm volatile("" : "+v"(l)); return wv * 64 + l; }
; DI int lbid() { int t = blockIdx.x; asm volatile("" : "+s"(t)); return t; }
; #define PG8_WAIT_V(n) asm volatile("s_waitcnt vmcnt(" #n ")" ::: "memory")
;     ...
;     const int tid = ltid(wv), wid = __builtin_amdgcn_readfirstlane(tid >> 6), lane = tid & 63, wr = wid >> 2, wc = wid & 3, fr = lane & 15, fq = lane >> 4;
;     const int nt = K / BK;
;     StaticOrder SO; { int c_ = lbid() - rot; if (c_ < 0) c_ += (int)gridDim.x; SO.init(nM, nN, (int)gridDim.x, c_); }
;     unsigned voffA[2], voffB[2];
; #pragma unroll
;     for (int i = 0; i < 2; ++i) { int R, C; stage_rc(tid * 16 + i * 8192, R, C); const int Rb = (R & ~31) + perm32(R & 31);
;         const int Ra = AMAP ? (62 * (R >> 6) + (R & 63) - 2) : R;
;         voffA[i] = (unsigned)((Ra + (AMAP ? 2 : 0)) * lda + C) * 2u; voffB[i] = (unsigned)(Rb * ldb + C) * 2u; }
;     const size_t kstep = (size_t)(BK * 2);
;     const size_t hstepA = (size_t)(AMAP ? 124 : 128) * lda * 2, hstepB = (size_t)HALF * ldb * 2;
;     const size_t tstepA = 2 * hstepA, tstepB = 2 * hstepB;
;     const unsigned ldsw = (unsigned)wid * 1024u;
;     const int aoff = lds_byte(wr * 64 + fr, fq * 8), boff = lds_byte(wc * 32 + fr, fq * 8);
;     ...
;     if (AMAP) A -= 2 * lda;
;     Unit cur, nxt; int ui = 0;
;     if (!SO.next(0, cur)) return;
;     f32x4 acc[2][2][4][2];
; #pragma unroll
;     for (int a = 0; a < 2; ++a)
; #pragma unroll
;         for (int b = 0; b < 2; ++b)
; #pragma unroll
;             for (int m = 0; m < 4; ++m)
; #pragma unroll
;                 for (int n = 0; n < 2; ++n) acc[a][b][m][n] = (f32x4){0.f, 0.f, 0.f, 0.f};
;     bf16x8 At[4][2], B0[2][2], B1[2][2];
;     const char* cA = (const char*)A + (size_t)cur.pm * tstepA + (KOFS ? (cur.pn & 1) * 512 : 0); const char* cB = (const char*)Bt + (size_t)cur.pn * tstepB + (KOFS ? (cur.pn & 1) * 512 : 0);
;     PG8_STAGE(PG8_SB(0, 0), cB, voffB); PG8_STAGE(PG8_SB(0, 1), cB + hstepB, voffB); PG8_STAGE(PG8_SA(0, 0), cA, voffA); PG8_STAGE(PG8_SA(0, 1), cA + hstepA, voffA);
;     if (wr == 1) PG8_BAR;
;     PG8_WAIT_V(2); PG8_BAR;
;     PG8_STAGE(PG8_SB(1, 0), cB + kstep, voffB); PG8_STAGE(PG8_SA(1, 0), cA + kstep, voffA); PG8_STAGE(PG8_SB(1, 1), cB + hstepB + kstep, voffB);
;     PG8_WAIT_V(6); PG8_BAR;
.LBB0_611:
	v_ashrrev_i32_e32 v2, 31, v0
	v_lshrrev_b32_e32 v2, 26, v2
	v_lshlrev_b32_e32 v1, 4, v0
	v_add_u32_e32 v2, v0, v2
	v_bfe_i32 v0, v0, 27, 1
	v_lshrrev_b32_e32 v0, 22, v0
	v_add_u32_e32 v0, v1, v0
	v_and_b32_e32 v0, 0xfffffc00, v0
	v_sub_u32_e32 v0, v1, v0
	v_ashrrev_i32_e32 v9, 6, v2
	v_lshrrev_b32_e32 v2, 4, v0
	v_bitop3_b32 v0, v2, v0, 32 bitop3:0x6c
	v_ashrrev_i32_e32 v3, 31, v0
	v_lshrrev_b32_e32 v3, 26, v3
	s_ashr_i32 s8, s13, 6
	v_add_u32_e32 v3, v0, v3
	s_ashr_i32 s10, s13, 8
	v_lshlrev_b32_e32 v2, 3, v9
	v_ashrrev_i32_e32 v10, 6, v3
	v_and_b32_e32 v3, 0xc0, v3
	s_lshl_b32 s29, s8, 10
	v_and_b32_e32 v2, -16, v2
	v_sub_u32_e32 v0, v0, v3
	v_mov_b32_e32 v3, 1
	s_waitcnt lgkmcnt(0)
	s_add_u32 s30, s6, 0x556ba00
	v_add_u32_e32 v2, v10, v2
	v_lshlrev_b32_e32 v4, 5, v9
	v_ashrrev_i16_sdwa v0, v3, sext(v0) dst_sel:DWORD dst_unused:UNUSED_PAD src0_sel:DWORD src1_sel:BYTE_0
	s_addc_u32 s31, s7, 0
	v_and_b32_e32 v11, 32, v4
	v_bfe_i32 v12, v0, 0, 16
	v_lshlrev_b32_e32 v4, 1, v2
	v_lshrrev_b32_e32 v5, 2, v2
	v_and_b32_e32 v6, 3, v10
	s_mov_b32 s15, 0x7fffe0
	s_movk_i32 s14, 0x600
	s_add_u32 s33, s4, 0x416b000
	v_add_u32_e32 v0, v11, v12
	v_and_b32_e32 v4, 24, v4
	v_and_b32_e32 v5, 4, v5
	v_and_or_b32 v6, v2, s15, v6
	v_mul_lo_u32 v2, v2, s14
	s_addc_u32 s34, s5, 0
	s_add_i32 s4, s11, s9
	v_or3_b32 v4, v6, v5, v4
	v_add_lshl_u32 v128, v0, v2, 1
	v_lshlrev_b32_e32 v0, 1, v0
	s_ashr_i32 s5, s4, 31
	v_lshl_add_u32 v130, v4, 9, v0
	v_add_u32_e32 v0, 0x2000, v1
	s_lshr_b32 s5, s5, 28
	v_ashrrev_i32_e32 v1, 31, v0
	s_add_i32 s5, s4, s5
	v_lshrrev_b32_e32 v1, 22, v1
	s_ashr_i32 s6, s5, 4
	s_and_b32 s5, s5, 0xfff0
	v_add_u32_e32 v1, v0, v1
	s_sub_i32 s5, s4, s5
	v_ashrrev_i32_e32 v13, 10, v1
	s_bfe_i32 s4, s5, 0x80000
	v_mul_i32_i24_e32 v1, 0x400, v13
	s_bfe_u32 s4, s4, 0x3000c
	v_sub_u32_e32 v0, v0, v1
	s_add_i32 s7, s5, s4
	v_lshrrev_b32_e32 v1, 4, v0
	s_bfe_i32 s4, s7, 0x80000
	s_and_b32 s7, s7, 0xf8
	v_bitop3_b32 v0, v1, v0, 32 bitop3:0x6c
	s_sub_i32 s5, s5, s7
	v_ashrrev_i32_e32 v2, 31, v0
	s_lshl_b32 s6, s6, 3
	s_sext_i32_i8 s5, s5
	v_lshrrev_b32_e32 v2, 26, v2
	s_sext_i32_i16 s4, s4
	s_add_i32 s51, s6, s5
	v_add_u32_e32 v2, v0, v2
	s_lshr_b32 s4, s4, 3
	s_mul_hi_i32 s5, s51, 0xc0000
	v_lshlrev_b32_e32 v1, 3, v13
	v_ashrrev_i32_e32 v14, 6, v2
	v_and_b32_e32 v2, 0xc0, v2
	s_bfe_i64 s[6:7], s[4:5], 0x100000
	v_and_b32_e32 v1, -16, v1
	v_sub_u32_e32 v0, v0, v2
	s_lshl_b64 s[6:7], s[6:7], 17
	v_add_u32_e32 v1, v14, v1
	v_lshlrev_b32_e32 v4, 5, v13
	v_ashrrev_i16_sdwa v0, v3, sext(v0) dst_sel:DWORD dst_unused:UNUSED_PAD src0_sel:DWORD src1_sel:BYTE_0
	s_add_u32 s22, s33, s6
	v_and_b32_e32 v15, 32, v4
	v_bfe_i32 v16, v0, 0, 16
	v_lshlrev_b32_e32 v2, 1, v1
	v_lshrrev_b32_e32 v3, 2, v1
	v_and_b32_e32 v4, 3, v14
	s_addc_u32 s23, s34, s7
	s_add_i32 s35, s29, 0
	v_add_u32_e32 v0, v15, v16
	v_and_b32_e32 v2, 24, v2
	v_and_b32_e32 v3, 4, v3
	v_and_or_b32 v4, v1, s15, v4
	v_mul_lo_u32 v1, v1, s14
	s_add_i32 m0, s35, 0x10000
	v_or3_b32 v2, v4, v3, v2
	v_add_lshl_u32 v132, v0, v1, 1
	v_lshlrev_b32_e32 v0, 1, v0
	global_load_lds_dwordx4 v130, s[22:23]
	s_add_i32 m0, s35, 0x12000
	v_lshl_add_u32 v134, v2, 9, v0
	s_add_u32 s6, s22, 0x10000
	global_load_lds_dwordx4 v134, s[22:23]
	s_addc_u32 s7, s23, 0
	s_add_i32 m0, s35, 0x14000
	s_mul_i32 s9, s51, 0xc0000
	global_load_lds_dwordx4 v130, s[6:7]
	s_add_i32 m0, s35, 0x16000
	s_add_u32 s20, s30, s9
	s_addc_u32 s21, s31, s5
	s_add_i32 s36, s35, 0x2000
	global_load_lds_dwordx4 v134, s[6:7]
	s_mov_b32 m0, s35
	s_add_u32 s6, s20, 0x60000
	global_load_lds_dwordx4 v128, s[20:21]
	s_mov_b32 m0, s36
	s_addc_u32 s7, s21, 0
	s_add_i32 s37, s35, 0x4000
	global_load_lds_dwordx4 v132, s[20:21]
	s_mov_b32 m0, s37
	s_add_i32 s38, s35, 0x6000
	global_load_lds_dwordx4 v128, s[6:7]
	s_mov_b32 m0, s38
	v_mov_b32_e32 v131, 0
	global_load_lds_dwordx4 v132, s[6:7]
	s_mov_b64 s[6:7], s[100:101]
	v_mov_b32_e32 v135, v131
	v_mov_b32_e32 v129, v131
	v_mov_b32_e32 v133, v131
	s_cmp_eq_u32 s10, 1
	s_movk_i32 s39, 0xc0
	s_mov_b32 s40, 0
	v_lshl_add_u64 v[6:7], s[22:23], 0, v[130:131]
	v_lshl_add_u64 v[4:5], s[22:23], 0, v[134:135]
	v_lshl_add_u64 v[2:3], s[20:21], 0, v[128:129]
	v_lshl_add_u64 v[0:1], s[20:21], 0, v[132:133]
	s_cselect_b64 s[0:1], -1, 0
	s_cmp_lg_u32 s10, 1
	s_movk_i32 s5, 0x6000
	s_cbranch_scc1 .LBB0_613
	s_barrier

; #define WSB (getargs().ws())
;     DI bool next(int i, Unit& u) const {
;         const long L = (long)i * G + c; if (L >= nwg) return false;
;         int wgid = (int)L; { const int q = nwg / NXCD, r = nwg % NXCD, xcd = wgid % NXCD, off = wgid / NXCD; wgid = (xcd < r ? xcd * (q + 1) : r * (q + 1) + (xcd - r) * q) + off; }
;         const int nig = WGM * nN, gid = wgid / nig, fm = gid * WGM, gsz = (nM - fm) < WGM ? (nM - fm) : WGM;
;         u.pm = fm + ((wgid % nig) % gsz); u.pn = (wgid % nig) / gsz; return true;
; __global__ void __launch_bounds__(512, 2) fwd_kernel(Args a_unused) {
;     ...
;     { EpiColBf16<2> E{(bf16_t*)(WSB + O_VT), S, (const float*)(WSB + O_RSKV)};
;       pg8::gemm_phase<false>(wv, lds, (const bf16_t*)(WSB + O_WVT), 256, (const bf16_t*)(WSB + O_Z) + 1280, 1536, 256, 2, 64, E, 64); }
.LBB0_635:
	s_cmpk_gt_i32 s38, 0x7f
	s_cbranch_scc1 .LBB0_663
	s_ashr_i32 s39, s38, 31
	s_mov_b64 s[6:7], s[100:101]
	s_mov_b64 s[0:1], s[100:101]
	s_lshr_b32 s2, s39, 29
	s_add_i32 s18, s38, s2
	s_and_b32 s2, s18, -8
	s_sub_i32 s17, s38, s2
	s_cmp_gt_i32 s17, -1
	s_cbranch_scc0 .LBB0_638
	s_lshl_b32 s16, s17, 4
	s_mov_b64 s[12:13], 0
	s_branch .LBB0_639

;     DI bool next(int i, Unit& u) const {
;         const long L = (long)i * G + c; if (L >= nwg) return false;
;         int wgid = (int)L; { const int q = nwg / NXCD, r = nwg % NXCD, xcd = wgid % NXCD, off = wgid / NXCD; wgid = (xcd < r ? xcd * (q + 1) : r * (q + 1) + (xcd - r) * q) + off; }
;         const int nig = WGM * nN, gid = wgid / nig, fm = gid * WGM, gsz = (nM - fm) < WGM ? (nM - fm) : WGM;
;         u.pm = fm + ((wgid % nig) % gsz); u.pn = (wgid % nig) / gsz; return true;
.LBB0_639:
	s_mov_b64 s[2:3], s[100:101]
	s_mov_b64 s[4:5], s[100:101]
	s_andn2_b64 vcc, exec, s[12:13]
	s_ashr_i32 s9, s18, 3
	s_cbranch_vccnz .LBB0_641
	s_mul_i32 s16, s17, 17

; #define LAS __attribute__((address_space(3)))
; DI int ltid(int wv) { asm volatile("" : "+s"(wv)); int l = __builtin_amdgcn_mbcnt_hi(~0u, __builtin_amdgcn_mbcnt_lo(~0u, 0u)); asm volatile("" : "+v"(l)); return wv * 64 + l; }
; DI unsigned xb_ld(unsigned* p) { return __hip_atomic_load(p, __ATOMIC_RELAXED, __HIP_MEMORY_SCOPE_AGENT); }
; DI unsigned xb_add(unsigned* p, unsigned v) { return __hip_atomic_fetch_add(p, v, __ATOMIC_RELAXED, __HIP_MEMORY_SCOPE_AGENT); }
; DI unsigned xb_xcc_id() { return (unsigned)__builtin_amdgcn_s_getreg((3 << 11) | 20) & 0xFu; }
; DI void xcd_barrier_complete(unsigned* bar, unsigned x, unsigned& nloc, unsigned& nx) {
;     const unsigned G = gridDim.x;
;     unsigned sum, cnt, mine, sp = 0u;
;     for (;;) {
;         sum = 0u; cnt = 0u; mine = 0u;
; #pragma unroll
;         for (unsigned j = 0; j < 16; ++j) { const unsigned c = xb_ld(&bar[XB_XCNT(j)]); sum += c; cnt += (c > 0u) ? 1u : 0u; mine = (j == x) ? c : mine; }
;         if (sum == G) break;
; DI void xcd_barrier(int wv, unsigned* bar, volatile LAS unsigned* st) {
;     asm volatile("s_waitcnt vmcnt(0)" ::: "memory");
;     __syncthreads();
;     if (ltid(wv) == 0) {
;         const unsigned x = xb_xcc_id();
;         __builtin_amdgcn_s_waitcnt(0);
;         unsigned nloc = st[0], nx = st[1];
;         if (nloc == 0u) { xcd_barrier_complete(bar, x, nloc, nx); st[0] = nloc; st[1] = nx; }
;         const unsigned old = xb_add(&bar[XB_XSUB(x)], 1u);
.LBB0_663:
	s_mov_b64 s[2:3], s[82:83]
	s_mov_b32 s0, s50
	s_waitcnt vmcnt(0)
	s_waitcnt vmcnt(0) lgkmcnt(0)
	s_barrier
	s_lshl_b32 s0, s0, 6
	v_mov_b32_e32 v0, v192
	s_sub_i32 s0, 0, s0
	s_nop 0
	v_cmp_eq_u32_e32 vcc, s0, v0
	s_and_saveexec_b64 s[0:1], vcc
	s_xor_b64 s[0:1], exec, s[0:1]
	s_cbranch_execz .LBB0_716
	s_add_i32 s5, 0, 0x22000
	v_mov_b32_e32 v0, s5
	s_mov_b64 s[2:3], s[100:101]
	s_getreg_b32 s4, hwreg(HW_REG_XCC_ID, 0, 4)
	s_waitcnt vmcnt(0) expcnt(0) lgkmcnt(0)
	ds_read_b32 v2, v0
	s_add_i32 s5, 0, 0x22004
	v_mov_b32_e32 v0, s5
	ds_read_b32 v0, v0
	s_and_b32 s33, s4, 15
	s_waitcnt lgkmcnt(1)
	v_cmp_ne_u32_e32 vcc, 0, v2
	s_cbranch_vccnz .LBB0_679
	s_add_u32 s4, s2, 0x1d83200
	s_addc_u32 s5, s3, 0
	s_add_u32 s6, s2, 0x1d83400
	s_addc_u32 s7, s3, 0
	s_add_u32 s8, s2, 0x1d83500
	s_addc_u32 s9, s3, 0
	s_add_u32 s10, s2, 0x1d83600
	s_addc_u32 s11, s3, 0
	s_add_u32 s12, s2, 0x1d83700
	s_addc_u32 s13, s3, 0
	s_add_u32 s14, s2, 0x1d83800
	s_addc_u32 s15, s3, 0
	s_add_u32 s16, s2, 0x1d83900
	s_addc_u32 s17, s3, 0
	s_add_u32 s18, s2, 0x1d83a00
	s_addc_u32 s19, s3, 0
	s_add_u32 s20, s2, 0x1d83b00
	s_addc_u32 s21, s3, 0
	s_add_u32 s22, s2, 0x1d83c00
	s_addc_u32 s23, s3, 0
	s_add_u32 s24, s2, 0x1d83d00
	s_addc_u32 s25, s3, 0
	s_add_u32 s26, s2, 0x1d83e00
	s_addc_u32 s27, s3, 0
	s_add_u32 s28, s2, 0x1d83f00
	s_addc_u32 s29, s3, 0
	s_add_u32 s30, s2, 0x1d84000
	s_addc_u32 s31, s3, 0
	s_add_u32 s34, s2, 0x1d84100
	s_load_dword s46, s[88:89], 0x0
	s_addc_u32 s35, s3, 0
	s_add_u32 s36, s2, 0x1d84200
	s_addc_u32 s37, s3, 0
	s_add_u32 s38, s2, 0x1d84300
	s_addc_u32 s39, s3, 0
	s_mov_b32 s47, 1
	v_mov_b32_e32 v16, 0
	s_branch .LBB0_667

; DI int ltid(int wv) { asm volatile("" : "+s"(wv)); int l = __builtin_amdgcn_mbcnt_hi(~0u, __builtin_amdgcn_mbcnt_lo(~0u, 0u)); asm volatile("" : "+v"(l)); return wv * 64 + l; }
; DI void phase_lru_s1(int wv, const ArgP a) {
;     unsigned char* ws = a.ws(); const int ch = ltid(wv);
;     const bf16_t* RI = (const bf16_t*)(ws + O_RI); const bf16_t* XC = (const bf16_t*)(ws + O_XC);
;     float* CHA = (float*)(ws + O_CHA); float* CHH = (float*)(ws + O_CHH);
;     const float ba = a.in(7)[ch], bx = a.in(9)[ch]; const float lam = a.in(10)[ch];
;     const float sp8 = 8.f * log1pf(expf(-lam));
;     for (int c = blockIdx.x; c < 256; c += gridDim.x) {
.LBB0_716:
	s_or_b64 exec, exec, s[0:1]
	s_cmpk_lt_i32 s80, 0x100
	s_cselect_b64 s[0:1], -1, 0
	s_mov_b64 s[10:11], s[82:83]
	s_mov_b32 s2, s50
	s_waitcnt lgkmcnt(0)
	v_mov_b32_e32 v0, v192
	s_and_b64 vcc, exec, s[0:1]
	s_barrier
	s_cbranch_vccz .LBB0_721
	s_load_dwordx4 s[4:7], s[10:11], 0x48
	v_lshl_add_u32 v0, s2, 6, v0
	v_ashrrev_i32_e32 v1, 31, v0
	v_lshlrev_b64 v[4:5], 2, v[0:1]
	s_mov_b32 s12, 0xbfb8aa3b
	s_waitcnt lgkmcnt(0)
	v_lshl_add_u64 v[2:3], s[6:7], 0, v[4:5]
	global_load_dword v9, v[2:3], off
	s_load_dwordx2 s[8:9], s[10:11], 0x38
	s_mov_b64 s[2:3], s[100:101]
	v_lshlrev_b64 v[2:3], 1, v[0:1]
	s_mov_b32 s13, 0x42ce8ed0
	s_mov_b32 s14, 0xc2b17218
	s_waitcnt lgkmcnt(0)
	v_lshl_add_u64 v[6:7], s[8:9], 0, v[4:5]
	global_load_dword v1, v[6:7], off
	v_lshl_add_u64 v[4:5], s[4:5], 0, v[4:5]
	v_mov_b32_e32 v10, 0x7f800000
	s_mov_b32 s15, 0x3f2aaaab
	s_mov_b32 s21, 0x3f317218
	v_mov_b32_e32 v11, 0x3ecc95a3
	s_mov_b32 s10, 0x7f800000
	s_load_dword s16, s[88:89], 0x0
	s_mov_b32 s11, 0x33800000
	s_add_u32 s6, s2, 0x1b40000
	s_addc_u32 s7, s3, 0
	s_add_u32 s8, s2, 0x1bc0000
	s_mov_b32 s17, 0x1d88000
	s_mov_b32 s18, 0x1d89000
	s_mov_b32 s19, 0x856c000
	s_mov_b32 s20, 0x1d8a000
	s_addc_u32 s9, s3, 0
	s_waitcnt vmcnt(1)
	v_mul_f32_e32 v6, 0xbfb8aa3b, v9
	v_rndne_f32_e32 v8, v6
	v_fma_f32 v7, v9, s12, -v6
	v_sub_f32_e32 v6, v6, v8
	v_cvt_i32_f32_e32 v12, v8
	global_load_dword v8, v[4:5], off
	v_fmamk_f32 v7, v9, 0xb2a5705f, v7
	v_add_f32_e32 v6, v6, v7
	v_exp_f32_e32 v6, v6
	v_cmp_nlt_f32_e32 vcc, s13, v9
	v_ldexp_f32 v4, v6, v12
	s_nop 0
	v_cndmask_b32_e32 v4, 0, v4, vcc
	v_cmp_ngt_f32_e32 vcc, s14, v9
	s_nop 1
	v_cndmask_b32_e32 v6, v10, v4, vcc
	v_add_f32_e32 v7, 1.0, v6
	v_cvt_f64_f32_e32 v[4:5], v7
	v_frexp_mant_f32_e32 v9, v7
	v_add_f32_e32 v12, -1.0, v7
	v_frexp_exp_i32_f64_e32 v4, v[4:5]
	v_cmp_gt_f32_e32 vcc, s15, v9
	v_sub_f32_e32 v5, v6, v12
	v_sub_f32_e32 v12, v12, v7
	v_subbrev_co_u32_e32 v4, vcc, 0, v4, vcc
	v_add_f32_e32 v9, 1.0, v12
	v_cvt_f32_i32_e32 v12, v4
	v_sub_u32_e32 v4, 0, v4
	v_add_f32_e32 v5, v5, v9
	v_ldexp_f32 v7, v7, v4
	v_ldexp_f32 v4, v5, v4
	v_add_f32_e32 v5, -1.0, v7
	v_add_f32_e32 v9, 1.0, v7
	v_add_f32_e32 v13, 1.0, v5
	v_add_f32_e32 v14, -1.0, v9
	v_mul_f32_e32 v15, 0x3f317218, v12
	v_sub_f32_e32 v13, v7, v13
	v_sub_f32_e32 v7, v7, v14
	v_fma_f32 v14, v12, s21, -v15
	v_add_f32_e32 v13, v4, v13
	v_add_f32_e32 v4, v4, v7
	v_fmamk_f32 v7, v12, 0xb102e308, v14
	v_add_f32_e32 v14, v9, v4
	v_rcp_f32_e32 v17, v14
	v_add_f32_e32 v16, v15, v7
	v_sub_f32_e32 v9, v9, v14
	v_add_f32_e32 v12, v5, v13
	v_add_f32_e32 v4, v4, v9
	v_sub_f32_e32 v9, v16, v15
	v_sub_f32_e32 v5, v5, v12
	v_sub_f32_e32 v7, v7, v9
	v_mul_f32_e32 v9, v12, v17
	v_add_f32_e32 v5, v13, v5
	v_mul_f32_e32 v13, v14, v9
	v_fma_f32 v15, v9, v14, -v13
	v_fmac_f32_e32 v15, v9, v4
	v_add_f32_e32 v18, v13, v15
	v_sub_f32_e32 v19, v12, v18
	v_sub_f32_e32 v12, v12, v19
	v_sub_f32_e32 v13, v18, v13
	v_sub_f32_e32 v12, v12, v18
	v_sub_f32_e32 v13, v13, v15
	v_add_f32_e32 v5, v5, v12
	v_add_f32_e32 v5, v13, v5
	v_add_f32_e32 v12, v19, v5
	v_mul_f32_e32 v13, v17, v12
	v_sub_f32_e32 v15, v19, v12
	v_mul_f32_e32 v19, v14, v13
	v_fma_f32 v14, v13, v14, -v19
	v_add_f32_e32 v18, v9, v13
	v_fmac_f32_e32 v14, v13, v4
	v_sub_f32_e32 v9, v18, v9
	v_add_f32_e32 v4, v19, v14
	v_sub_f32_e32 v9, v13, v9
	v_sub_f32_e32 v13, v12, v4
	v_sub_f32_e32 v12, v12, v13
	v_add_f32_e32 v5, v5, v15
	v_sub_f32_e32 v15, v4, v19
	v_sub_f32_e32 v4, v12, v4
	v_sub_f32_e32 v14, v15, v14
	v_add_f32_e32 v4, v5, v4
	v_add_f32_e32 v4, v14, v4
	v_add_f32_e32 v4, v13, v4
	v_mul_f32_e32 v4, v17, v4
	v_add_f32_e32 v4, v9, v4
	v_add_f32_e32 v5, v18, v4
	v_mul_f32_e32 v12, v5, v5
	v_fmac_f32_e32 v11, 0x3e9b6dac, v12
	v_ldexp_f32 v9, v5, 1
	v_sub_f32_e32 v13, v5, v18
	v_mul_f32_e32 v5, v5, v12
	v_fmaak_f32 v11, v12, v11, 0x3f2aaada
	v_mul_f32_e32 v5, v5, v11
	v_add_f32_e32 v11, v9, v5
	v_sub_f32_e32 v4, v4, v13
	v_sub_f32_e32 v9, v11, v9
	v_ldexp_f32 v4, v4, 1
	v_sub_f32_e32 v5, v5, v9
	v_add_f32_e32 v4, v4, v5
	v_add_f32_e32 v5, v11, v4
	v_add_f32_e32 v9, v16, v5
	v_sub_f32_e32 v11, v5, v11
	v_sub_f32_e32 v4, v4, v11
	v_sub_f32_e32 v11, v9, v16
	v_sub_f32_e32 v5, v5, v11
	v_sub_f32_e32 v11, v9, v11
	v_add_f32_e32 v12, v7, v4
	v_sub_f32_e32 v11, v16, v11
	v_sub_f32_e32 v13, v12, v7
	v_add_f32_e32 v5, v5, v11
	v_sub_f32_e32 v11, v12, v13
	v_add_f32_e32 v5, v12, v5
	v_sub_f32_e32 v4, v4, v13
	v_sub_f32_e32 v7, v7, v11
	v_add_f32_e32 v11, v9, v5
	v_add_f32_e32 v4, v4, v7
	v_sub_f32_e32 v7, v11, v9
	v_sub_f32_e32 v5, v5, v7
	v_add_f32_e32 v4, v4, v5
	v_add_f32_e32 v4, v11, v4
	v_cmp_neq_f32_e32 vcc, s10, v6
	s_mov_b32 s10, s80
	s_nop 0
	v_cndmask_b32_e32 v4, v10, v4, vcc
	v_cmp_lt_f32_e64 vcc, |v6|, s11
	s_nop 1
	v_cndmask_b32_e32 v4, v4, v6, vcc
	v_mul_f32_e32 v9, 0xc1000000, v4

; #define LAS __attribute__((address_space(3)))
; DI int ltid(int wv) { asm volatile("" : "+s"(wv)); int l = __builtin_amdgcn_mbcnt_hi(~0u, __builtin_amdgcn_mbcnt_lo(~0u, 0u)); asm volatile("" : "+v"(l)); return wv * 64 + l; }
; DI unsigned xb_ld(unsigned* p) { return __hip_atomic_load(p, __ATOMIC_RELAXED, __HIP_MEMORY_SCOPE_AGENT); }
; DI unsigned xb_add(unsigned* p, unsigned v) { return __hip_atomic_fetch_add(p, v, __ATOMIC_RELAXED, __HIP_MEMORY_SCOPE_AGENT); }
; DI unsigned xb_xcc_id() { return (unsigned)__builtin_amdgcn_s_getreg((3 << 11) | 20) & 0xFu; }
; DI void xcd_barrier_complete(unsigned* bar, unsigned x, unsigned& nloc, unsigned& nx) {
;     const unsigned G = gridDim.x;
;     unsigned sum, cnt, mine, sp = 0u;
;     for (;;) {
;         sum = 0u; cnt = 0u; mine = 0u;
; #pragma unroll
;         for (unsigned j = 0; j < 16; ++j) { const unsigned c = xb_ld(&bar[XB_XCNT(j)]); sum += c; cnt += (c > 0u) ? 1u : 0u; mine = (j == x) ? c : mine; }
;         if (sum == G) break;
; DI void xcd_barrier(int wv, unsigned* bar, volatile LAS unsigned* st) {
;     asm volatile("s_waitcnt vmcnt(0)" ::: "memory");
;     __syncthreads();
;     if (ltid(wv) == 0) {
;         const unsigned x = xb_xcc_id();
;         __builtin_amdgcn_s_waitcnt(0);
;         unsigned nloc = st[0], nx = st[1];
;         if (nloc == 0u) { xcd_barrier_complete(bar, x, nloc, nx); st[0] = nloc; st[1] = nx; }
;         const unsigned old = xb_add(&bar[XB_XSUB(x)], 1u);
.LBB0_721:
	s_mov_b64 s[4:5], s[82:83]
	s_mov_b32 s2, s50
	s_waitcnt vmcnt(0)
	s_barrier
	s_lshl_b32 s2, s2, 6
	v_mov_b32_e32 v0, v192
	s_sub_i32 s2, 0, s2
	s_nop 0
	v_cmp_eq_u32_e32 vcc, s2, v0
	s_and_saveexec_b64 s[2:3], vcc
	s_xor_b64 s[2:3], exec, s[2:3]
	s_cbranch_execz .LBB0_774
	s_add_i32 s7, 0, 0x22000
	v_mov_b32_e32 v0, s7
	s_mov_b64 s[4:5], s[100:101]
	s_getreg_b32 s6, hwreg(HW_REG_XCC_ID, 0, 4)
	s_waitcnt vmcnt(0) expcnt(0) lgkmcnt(0)
	ds_read_b32 v2, v0
	s_add_i32 s7, 0, 0x22004
	v_mov_b32_e32 v0, s7
	ds_read_b32 v0, v0
	s_and_b32 s33, s6, 15
	s_waitcnt lgkmcnt(1)
	v_cmp_ne_u32_e32 vcc, 0, v2
	s_cbranch_vccnz .LBB0_737
	s_add_u32 s6, s4, 0x1d83200
	s_addc_u32 s7, s5, 0
	s_add_u32 s8, s4, 0x1d83400
	s_addc_u32 s9, s5, 0
	s_add_u32 s10, s4, 0x1d83500
	s_addc_u32 s11, s5, 0
	s_add_u32 s12, s4, 0x1d83600
	s_addc_u32 s13, s5, 0
	s_add_u32 s14, s4, 0x1d83700
	s_addc_u32 s15, s5, 0
	s_add_u32 s16, s4, 0x1d83800
	s_addc_u32 s17, s5, 0
	s_add_u32 s18, s4, 0x1d83900
	s_addc_u32 s19, s5, 0
	s_add_u32 s20, s4, 0x1d83a00
	s_addc_u32 s21, s5, 0
	s_add_u32 s22, s4, 0x1d83b00
	s_addc_u32 s23, s5, 0
	s_add_u32 s24, s4, 0x1d83c00
	s_addc_u32 s25, s5, 0
	s_add_u32 s26, s4, 0x1d83d00
	s_addc_u32 s27, s5, 0
	s_add_u32 s28, s4, 0x1d83e00
	s_addc_u32 s29, s5, 0
	s_add_u32 s30, s4, 0x1d83f00
	s_addc_u32 s31, s5, 0
	s_add_u32 s34, s4, 0x1d84000
	s_addc_u32 s35, s5, 0
	s_add_u32 s36, s4, 0x1d84100
	s_load_dword s49, s[88:89], 0x0
	s_addc_u32 s37, s5, 0
	s_add_u32 s38, s4, 0x1d84200
	s_addc_u32 s39, s5, 0
	s_add_u32 s40, s4, 0x1d84300
	s_addc_u32 s41, s5, 0
	s_mov_b32 s50, 1
	v_mov_b32_e32 v16, 0
	s_branch .LBB0_725

; DI int ltid(int wv) { asm volatile("" : "+s"(wv)); int l = __builtin_amdgcn_mbcnt_hi(~0u, __builtin_amdgcn_mbcnt_lo(~0u, 0u)); asm volatile("" : "+v"(l)); return wv * 64 + l; }
; DI void phase_lru_s3(int wv, const ArgP a) {
;     unsigned char* ws = a.ws(); const int ch = ltid(wv);
;     const bf16_t* RI = (const bf16_t*)(ws + O_RI); const bf16_t* XC = (const bf16_t*)(ws + O_XC); const bf16_t* Z = (const bf16_t*)(ws + O_Z);
;     const float* CHA = (const float*)(ws + O_CHA); const float* CHH = (const float*)(ws + O_CHH); bf16_t* MIX = (bf16_t*)(ws + O_MIX);
;     const float ba = a.in(7)[ch], bx = a.in(9)[ch]; const float lam = a.in(10)[ch];
;     const float sp8 = 8.f * log1pf(expf(-lam));
;     for (int c = blockIdx.x; c < 256; c += gridDim.x) {
.LBB0_774:
	s_or_b64 exec, exec, s[2:3]
	s_mov_b64 s[10:11], s[82:83]
	s_mov_b32 s2, s50
	s_waitcnt lgkmcnt(0)
	v_mov_b32_e32 v0, v192
	s_and_b64 vcc, exec, s[0:1]
	s_barrier
	s_cbranch_vccz .LBB0_785
	s_load_dwordx4 s[4:7], s[10:11], 0x48
	v_lshl_add_u32 v0, s2, 6, v0
	v_ashrrev_i32_e32 v1, 31, v0
	v_lshlrev_b64 v[4:5], 2, v[0:1]
	s_mov_b32 s12, 0xbfb8aa3b
	s_waitcnt lgkmcnt(0)
	v_lshl_add_u64 v[2:3], s[6:7], 0, v[4:5]
	global_load_dword v8, v[2:3], off
	s_load_dwordx2 s[8:9], s[10:11], 0x38
	s_mov_b64 s[2:3], s[100:101]
	v_lshlrev_b64 v[2:3], 1, v[0:1]
	s_mov_b32 s13, 0x42ce8ed0
	s_mov_b32 s14, 0xc2b17218
	s_waitcnt lgkmcnt(0)
	v_lshl_add_u64 v[6:7], s[8:9], 0, v[4:5]
	v_lshl_add_u64 v[4:5], s[4:5], 0, v[4:5]
	global_load_dword v1, v[6:7], off
	global_load_dword v15, v[4:5], off
	v_mov_b32_e32 v9, 0x7f800000
	s_mov_b32 s15, 0x3f2aaaab
	s_mov_b32 s16, 0x3f317218
	v_mov_b32_e32 v10, 0x3ecc95a3
	s_mov_b32 s10, 0x7f800000
	s_load_dword s18, s[88:89], 0x0
	s_mov_b32 s11, 0x33800000
	s_add_u32 s6, s2, 0x1b40000
	s_addc_u32 s7, s3, 0
	s_add_u32 s8, s2, 0x1bc0000
	s_mov_b32 s19, 0x556b000
	s_mov_b32 s20, 0xd56b000
	s_mov_b32 s21, 0x556c000
	s_mov_b32 s22, 0x1d88000
	s_mov_b32 s23, 0xd56c000
	s_mov_b32 s24, 0x556d000
	v_add_u32_e32 v14, 0x3600, v0
	s_addc_u32 s9, s3, 0
	s_waitcnt vmcnt(2)
	v_mul_f32_e32 v6, 0xbfb8aa3b, v8
	v_fma_f32 v7, v8, s12, -v6
	v_rndne_f32_e32 v11, v6
	v_fmamk_f32 v7, v8, 0xb2a5705f, v7
	v_sub_f32_e32 v6, v6, v11
	v_add_f32_e32 v6, v6, v7
	v_cvt_i32_f32_e32 v11, v11
	v_exp_f32_e32 v6, v6
	v_cmp_nlt_f32_e32 vcc, s13, v8
	v_ldexp_f32 v4, v6, v11
	s_nop 0
	v_cndmask_b32_e32 v4, 0, v4, vcc
	v_cmp_ngt_f32_e32 vcc, s14, v8
	s_nop 1
	v_cndmask_b32_e32 v6, v9, v4, vcc
	v_add_f32_e32 v7, 1.0, v6
	v_cvt_f64_f32_e32 v[4:5], v7
	v_frexp_mant_f32_e32 v8, v7
	v_add_f32_e32 v11, -1.0, v7
	v_frexp_exp_i32_f64_e32 v4, v[4:5]
	v_cmp_gt_f32_e32 vcc, s15, v8
	v_sub_f32_e32 v5, v6, v11
	v_sub_f32_e32 v11, v11, v7
	v_subbrev_co_u32_e32 v4, vcc, 0, v4, vcc
	v_add_f32_e32 v8, 1.0, v11
	v_cvt_f32_i32_e32 v11, v4
	v_sub_u32_e32 v4, 0, v4
	v_add_f32_e32 v5, v5, v8
	v_ldexp_f32 v7, v7, v4
	v_ldexp_f32 v4, v5, v4
	v_add_f32_e32 v5, -1.0, v7
	v_add_f32_e32 v8, 1.0, v7
	v_add_f32_e32 v12, 1.0, v5
	v_add_f32_e32 v13, -1.0, v8
	v_mul_f32_e32 v16, 0x3f317218, v11
	v_sub_f32_e32 v12, v7, v12
	v_sub_f32_e32 v7, v7, v13
	v_fma_f32 v13, v11, s16, -v16
	v_add_f32_e32 v12, v4, v12
	v_add_f32_e32 v4, v4, v7
	v_fmamk_f32 v7, v11, 0xb102e308, v13
	v_add_f32_e32 v13, v8, v4
	v_rcp_f32_e32 v18, v13
	v_add_f32_e32 v17, v16, v7
	v_sub_f32_e32 v8, v8, v13
	v_add_f32_e32 v11, v5, v12
	v_add_f32_e32 v4, v4, v8
	v_sub_f32_e32 v8, v17, v16
	v_sub_f32_e32 v5, v5, v11
	v_sub_f32_e32 v7, v7, v8
	v_mul_f32_e32 v8, v11, v18
	v_add_f32_e32 v5, v12, v5
	v_mul_f32_e32 v12, v13, v8
	v_fma_f32 v16, v8, v13, -v12
	v_fmac_f32_e32 v16, v8, v4
	v_add_f32_e32 v19, v12, v16
	v_sub_f32_e32 v20, v11, v19
	v_sub_f32_e32 v11, v11, v20
	v_sub_f32_e32 v12, v19, v12
	v_sub_f32_e32 v11, v11, v19
	v_sub_f32_e32 v12, v12, v16
	v_add_f32_e32 v5, v5, v11
	v_add_f32_e32 v5, v12, v5
	v_add_f32_e32 v11, v20, v5
	v_mul_f32_e32 v12, v18, v11
	v_sub_f32_e32 v16, v20, v11
	v_mul_f32_e32 v20, v13, v12
	v_fma_f32 v13, v12, v13, -v20
	v_add_f32_e32 v19, v8, v12
	v_fmac_f32_e32 v13, v12, v4
	v_sub_f32_e32 v8, v19, v8
	v_add_f32_e32 v4, v20, v13
	v_sub_f32_e32 v8, v12, v8
	v_sub_f32_e32 v12, v11, v4
	v_sub_f32_e32 v11, v11, v12
	v_add_f32_e32 v5, v5, v16
	v_sub_f32_e32 v16, v4, v20
	v_sub_f32_e32 v4, v11, v4
	v_sub_f32_e32 v13, v16, v13
	v_add_f32_e32 v4, v5, v4
	v_add_f32_e32 v4, v13, v4
	v_add_f32_e32 v4, v12, v4
	v_mul_f32_e32 v4, v18, v4
	v_add_f32_e32 v4, v8, v4
	v_add_f32_e32 v5, v19, v4
	v_mul_f32_e32 v11, v5, v5
	v_fmac_f32_e32 v10, 0x3e9b6dac, v11
	v_ldexp_f32 v8, v5, 1
	v_sub_f32_e32 v12, v5, v19
	v_mul_f32_e32 v5, v5, v11
	v_fmaak_f32 v10, v11, v10, 0x3f2aaada
	v_mul_f32_e32 v5, v5, v10
	v_add_f32_e32 v10, v8, v5
	v_sub_f32_e32 v4, v4, v12
	v_sub_f32_e32 v8, v10, v8
	v_ldexp_f32 v4, v4, 1
	v_sub_f32_e32 v5, v5, v8
	v_add_f32_e32 v4, v4, v5
	v_add_f32_e32 v5, v10, v4
	v_add_f32_e32 v8, v17, v5
	v_sub_f32_e32 v10, v5, v10
	v_sub_f32_e32 v4, v4, v10
	v_sub_f32_e32 v10, v8, v17
	v_sub_f32_e32 v5, v5, v10
	v_sub_f32_e32 v10, v8, v10
	v_add_f32_e32 v11, v7, v4
	v_sub_f32_e32 v10, v17, v10
	v_sub_f32_e32 v12, v11, v7
	v_add_f32_e32 v5, v5, v10
	v_sub_f32_e32 v10, v11, v12
	v_add_f32_e32 v5, v11, v5
	v_sub_f32_e32 v4, v4, v12
	v_sub_f32_e32 v7, v7, v10
	v_add_f32_e32 v10, v8, v5
	v_add_f32_e32 v4, v4, v7
	v_sub_f32_e32 v7, v10, v8
	v_sub_f32_e32 v5, v5, v7
	v_add_f32_e32 v4, v4, v5
	v_add_f32_e32 v4, v10, v4
	v_cmp_neq_f32_e32 vcc, s10, v6
	s_mov_b32 s10, s80
	s_nop 0
	v_cndmask_b32_e32 v4, v9, v4, vcc
	v_cmp_lt_f32_e64 vcc, |v6|, s11
	s_nop 1
	v_cndmask_b32_e32 v4, v4, v6, vcc
	v_mul_f32_e32 v16, 0xc1000000, v4

; #define LAS __attribute__((address_space(3)))
; DI void phase_attn(int wv, const ArgP a, LAS unsigned char* lds) {
;     unsigned char* ws = a.ws();
;     const bf16_t* QB = (const bf16_t*)(ws + O_QB); const bf16_t* KB = (const bf16_t*)(ws + O_KB); const bf16_t* VT = (const bf16_t*)(ws + O_VT); bf16_t* MIX = (bf16_t*)(ws + O_MIX);
;     if (wv >= 4) __builtin_amdgcn_s_setprio(1);
.LBB0_785:
	s_mov_b64 s[2:3], s[82:83]
	s_mov_b64 s[94:95], s[100:101]
	s_cmpk_gt_u32 s48, 0xff
	s_cbranch_scc0 .LBB0_787
	s_setprio 1

; #define LAS __attribute__((address_space(3)))
; DI int ltid(int wv) { asm volatile("" : "+s"(wv)); int l = __builtin_amdgcn_mbcnt_hi(~0u, __builtin_amdgcn_mbcnt_lo(~0u, 0u)); asm volatile("" : "+v"(l)); return wv * 64 + l; }
; DI unsigned xb_ld(unsigned* p) { return __hip_atomic_load(p, __ATOMIC_RELAXED, __HIP_MEMORY_SCOPE_AGENT); }
; DI unsigned xb_add(unsigned* p, unsigned v) { return __hip_atomic_fetch_add(p, v, __ATOMIC_RELAXED, __HIP_MEMORY_SCOPE_AGENT); }
; DI unsigned xb_xcc_id() { return (unsigned)__builtin_amdgcn_s_getreg((3 << 11) | 20) & 0xFu; }
; DI void xcd_barrier_complete(unsigned* bar, unsigned x, unsigned& nloc, unsigned& nx) {
;     const unsigned G = gridDim.x;
;     unsigned sum, cnt, mine, sp = 0u;
;     for (;;) {
;         sum = 0u; cnt = 0u; mine = 0u;
; #pragma unroll
;         for (unsigned j = 0; j < 16; ++j) { const unsigned c = xb_ld(&bar[XB_XCNT(j)]); sum += c; cnt += (c > 0u) ? 1u : 0u; mine = (j == x) ? c : mine; }
;         if (sum == G) break;
; DI void xcd_barrier(int wv, unsigned* bar, volatile LAS unsigned* st) {
;     asm volatile("s_waitcnt vmcnt(0)" ::: "memory");
;     __syncthreads();
;     if (ltid(wv) == 0) {
;         const unsigned x = xb_xcc_id();
;         __builtin_amdgcn_s_waitcnt(0);
;         unsigned nloc = st[0], nx = st[1];
;         if (nloc == 0u) { xcd_barrier_complete(bar, x, nloc, nx); st[0] = nloc; st[1] = nx; }
;         const unsigned old = xb_add(&bar[XB_XSUB(x)], 1u);
.LBB0_945:
	s_setprio 0
	s_mov_b64 s[2:3], s[82:83]
	s_mov_b32 s0, s50
	s_waitcnt vmcnt(0)
	s_waitcnt lgkmcnt(0)
	s_barrier
	s_lshl_b32 s0, s0, 6
	v_mov_b32_e32 v0, v192
	s_sub_i32 s0, 0, s0
	s_nop 0
	v_cmp_eq_u32_e32 vcc, s0, v0
	s_and_saveexec_b64 s[0:1], vcc
	s_xor_b64 s[0:1], exec, s[0:1]
	s_cbranch_execz .LBB0_998
	s_add_i32 s5, 0, 0x22000
	v_mov_b32_e32 v0, s5
	s_mov_b64 s[2:3], s[100:101]
	s_getreg_b32 s4, hwreg(HW_REG_XCC_ID, 0, 4)
	s_waitcnt vmcnt(0) expcnt(0) lgkmcnt(0)
	ds_read_b32 v2, v0
	s_add_i32 s5, 0, 0x22004
	v_mov_b32_e32 v0, s5
	ds_read_b32 v0, v0
	s_and_b32 s33, s4, 15
	s_waitcnt lgkmcnt(1)
	v_cmp_ne_u32_e32 vcc, 0, v2
	s_cbranch_vccnz .LBB0_961
	s_add_u32 s4, s2, 0x1d83200
	s_addc_u32 s5, s3, 0
	s_add_u32 s6, s2, 0x1d83400
	s_addc_u32 s7, s3, 0
	s_add_u32 s8, s2, 0x1d83500
	s_addc_u32 s9, s3, 0
	s_add_u32 s10, s2, 0x1d83600
	s_addc_u32 s11, s3, 0
	s_add_u32 s12, s2, 0x1d83700
	s_addc_u32 s13, s3, 0
	s_add_u32 s14, s2, 0x1d83800
	s_addc_u32 s15, s3, 0
	s_add_u32 s16, s2, 0x1d83900
	s_addc_u32 s17, s3, 0
	s_add_u32 s18, s2, 0x1d83a00
	s_addc_u32 s19, s3, 0
	s_add_u32 s20, s2, 0x1d83b00
	s_addc_u32 s21, s3, 0
	s_add_u32 s22, s2, 0x1d83c00
	s_addc_u32 s23, s3, 0
	s_add_u32 s24, s2, 0x1d83d00
	s_addc_u32 s25, s3, 0
	s_add_u32 s26, s2, 0x1d83e00
	s_addc_u32 s27, s3, 0
	s_add_u32 s28, s2, 0x1d83f00
	s_addc_u32 s29, s3, 0
	s_add_u32 s30, s2, 0x1d84000
	s_addc_u32 s31, s3, 0
	s_add_u32 s34, s2, 0x1d84100
	s_load_dword s46, s[88:89], 0x0
	s_addc_u32 s35, s3, 0
	s_add_u32 s36, s2, 0x1d84200
	s_addc_u32 s37, s3, 0
	s_add_u32 s38, s2, 0x1d84300
	s_addc_u32 s39, s3, 0
	s_mov_b32 s47, 1
	v_mov_b32_e32 v16, 0
	s_branch .LBB0_949

; DI ArgP getargs() { ArgP r; r.p = (const __attribute__((address_space(4))) Args*)__builtin_amdgcn_kernarg_segment_ptr(); asm volatile("" : "+s"(r.p)); return r; }
; #define WSB (getargs().ws())
;     DI bool next(int i, Unit& u) const {
;         const long L = (long)i * G + c; if (L >= nwg) return false;
;         int wgid = (int)L; { const int q = nwg / NXCD, r = nwg % NXCD, xcd = wgid % NXCD, off = wgid / NXCD; wgid = (xcd < r ? xcd * (q + 1) : r * (q + 1) + (xcd - r) * q) + off; }
;         const int nig = WGM * nN, gid = wgid / nig, fm = gid * WGM, gsz = (nM - fm) < WGM ? (nM - fm) : WGM;
;         u.pm = fm + ((wgid % nig) % gsz); u.pn = (wgid % nig) / gsz; return true;
; __global__ void __launch_bounds__(512, 2) fwd_kernel(Args a_unused) {
;     ...
;     { EpiRes<false> E{getargs().in(0), XBP, RSS + 1 * S, dry_};
;       pg8::gemm_phase<false>(wv, lds, (const bf16_t*)(WSB + O_MIX), 1024, (const bf16_t*)(WSB + O_WO1T), 1024, 1024, 64, 4, E); }
.LBB0_1000:
	s_load_dwordx2 s[0:1], s[10:11], 0x0
	s_mov_b64 s[4:5], s[100:101]
	s_mov_b64 s[6:7], s[100:101]
	s_mov_b64 s[8:9], s[100:101]
	s_mov_b64 s[2:3], s[100:101]
	s_ashr_i32 s39, s33, 31
	s_cmpk_lt_i32 s33, 0x100
	s_cselect_b64 s[10:11], -1, 0
	s_cmpk_gt_i32 s33, 0xff
	s_cbranch_scc1 .LBB0_1006
	s_ashr_i32 s12, s33, 31
	s_lshr_b32 s12, s12, 29
	s_add_i32 s16, s33, s12
	s_and_b32 s12, s16, -8
	s_sub_i32 s14, s33, s12
	s_cmp_gt_i32 s14, -1
	s_cbranch_scc0 .LBB0_1003
	s_lshl_b32 s15, s14, 5
	s_ashr_i32 s12, s16, 3
	s_cbranch_execz .LBB0_1004
	s_branch .LBB0_1005

; #define LAS __attribute__((address_space(3)))
; DI int ltid(int wv) { asm volatile("" : "+s"(wv)); int l = __builtin_amdgcn_mbcnt_hi(~0u, __builtin_amdgcn_mbcnt_lo(~0u, 0u)); asm volatile("" : "+v"(l)); return wv * 64 + l; }
; DI unsigned xb_ld(unsigned* p) { return __hip_atomic_load(p, __ATOMIC_RELAXED, __HIP_MEMORY_SCOPE_AGENT); }
; DI unsigned xb_add(unsigned* p, unsigned v) { return __hip_atomic_fetch_add(p, v, __ATOMIC_RELAXED, __HIP_MEMORY_SCOPE_AGENT); }
; DI unsigned xb_xcc_id() { return (unsigned)__builtin_amdgcn_s_getreg((3 << 11) | 20) & 0xFu; }
; DI void xcd_barrier_complete(unsigned* bar, unsigned x, unsigned& nloc, unsigned& nx) {
;     const unsigned G = gridDim.x;
;     unsigned sum, cnt, mine, sp = 0u;
;     for (;;) {
;         sum = 0u; cnt = 0u; mine = 0u;
; #pragma unroll
;         for (unsigned j = 0; j < 16; ++j) { const unsigned c = xb_ld(&bar[XB_XCNT(j)]); sum += c; cnt += (c > 0u) ? 1u : 0u; mine = (j == x) ? c : mine; }
;         if (sum == G) break;
; DI void xcd_barrier(int wv, unsigned* bar, volatile LAS unsigned* st) {
;     asm volatile("s_waitcnt vmcnt(0)" ::: "memory");
;     __syncthreads();
;     if (ltid(wv) == 0) {
;         const unsigned x = xb_xcc_id();
;         __builtin_amdgcn_s_waitcnt(0);
;         unsigned nloc = st[0], nx = st[1];
;         if (nloc == 0u) { xcd_barrier_complete(bar, x, nloc, nx); st[0] = nloc; st[1] = nx; }
;         const unsigned old = xb_add(&bar[XB_XSUB(x)], 1u);
.LBB0_1043:
	s_waitcnt lgkmcnt(0)
	s_mov_b64 s[2:3], s[82:83]
	s_mov_b32 s0, s50
	s_waitcnt vmcnt(0)
	s_barrier
	s_lshl_b32 s0, s0, 6
	v_mov_b32_e32 v0, v192
	s_sub_i32 s0, 0, s0
	s_nop 0
	v_cmp_eq_u32_e32 vcc, s0, v0
	s_and_saveexec_b64 s[0:1], vcc
	s_xor_b64 s[0:1], exec, s[0:1]
	s_cbranch_execz .LBB0_1096
	s_add_i32 s5, 0, 0x22000
	v_mov_b32_e32 v0, s5
	s_mov_b64 s[2:3], s[100:101]
	s_getreg_b32 s4, hwreg(HW_REG_XCC_ID, 0, 4)
	s_waitcnt vmcnt(0) expcnt(0) lgkmcnt(0)
	ds_read_b32 v2, v0
	s_add_i32 s5, 0, 0x22004
	v_mov_b32_e32 v0, s5
	ds_read_b32 v0, v0
	s_and_b32 s33, s4, 15
	s_waitcnt lgkmcnt(1)
	v_cmp_ne_u32_e32 vcc, 0, v2
	s_cbranch_vccnz .LBB0_1059
	s_add_u32 s4, s2, 0x1d83200
	s_addc_u32 s5, s3, 0
	s_add_u32 s6, s2, 0x1d83400
	s_addc_u32 s7, s3, 0
	s_add_u32 s8, s2, 0x1d83500
	s_addc_u32 s9, s3, 0
	s_add_u32 s10, s2, 0x1d83600
	s_addc_u32 s11, s3, 0
	s_add_u32 s12, s2, 0x1d83700
	s_addc_u32 s13, s3, 0
	s_add_u32 s14, s2, 0x1d83800
	s_addc_u32 s15, s3, 0
	s_add_u32 s16, s2, 0x1d83900
	s_addc_u32 s17, s3, 0
	s_add_u32 s18, s2, 0x1d83a00
	s_addc_u32 s19, s3, 0
	s_add_u32 s20, s2, 0x1d83b00
	s_addc_u32 s21, s3, 0
	s_add_u32 s22, s2, 0x1d83c00
	s_addc_u32 s23, s3, 0
	s_add_u32 s24, s2, 0x1d83d00
	s_addc_u32 s25, s3, 0
	s_add_u32 s26, s2, 0x1d83e00
	s_addc_u32 s27, s3, 0
	s_add_u32 s28, s2, 0x1d83f00
	s_addc_u32 s29, s3, 0
	s_add_u32 s30, s2, 0x1d84000
	s_addc_u32 s31, s3, 0
	s_add_u32 s34, s2, 0x1d84100
	s_load_dword s46, s[88:89], 0x0
	s_addc_u32 s35, s3, 0
	s_add_u32 s36, s2, 0x1d84200
	s_addc_u32 s37, s3, 0
	s_add_u32 s38, s2, 0x1d84300
	s_addc_u32 s39, s3, 0
	s_mov_b32 s47, 1
	v_mov_b32_e32 v16, 0
	s_branch .LBB0_1047

; DI ArgP getargs() { ArgP r; r.p = (const __attribute__((address_space(4))) Args*)__builtin_amdgcn_kernarg_segment_ptr(); asm volatile("" : "+s"(r.p)); return r; }
; #define WSB (getargs().ws())
;     DI bool next(int i, Unit& u) const {
;         const long L = (long)i * G + c; if (L >= nwg) return false;
;         int wgid = (int)L; { const int q = nwg / NXCD, r = nwg % NXCD, xcd = wgid % NXCD, off = wgid / NXCD; wgid = (xcd < r ? xcd * (q + 1) : r * (q + 1) + (xcd - r) * q) + off; }
;         const int nig = WGM * nN, gid = wgid / nig, fm = gid * WGM, gsz = (nM - fm) < WGM ? (nM - fm) : WGM;
;         u.pm = fm + ((wgid % nig) % gsz); u.pn = (wgid % nig) / gsz; return true;
; __global__ void __launch_bounds__(512, 2) fwd_kernel(Args a_unused) {
;     ...
;     { EpiUp E{(bf16_t*)(WSB + O_ACT), RSS + 1 * S, getargs().in(24), getargs().in(25), lds + 131072};
;       pg8::gemm_phase<true>(wv, lds, XBP, 1024, (const bf16_t*)(WSB + O_WUPT0), 1024, 1024, 67, 22, E); }
.LBB0_1099:
	s_ashr_i32 s33, s30, 31
	s_mov_b64 s[10:11], s[100:101]
	s_mov_b64 s[2:3], s[100:101]
	s_lshr_b32 s4, s33, 29
	s_add_i32 s24, s30, s4
	s_and_b32 s4, s24, -8
	s_sub_i32 s23, s30, s4
	s_cmp_gt_i32 s23, 1
	s_cbranch_scc0 .LBB0_1101
	s_mul_i32 s4, s23, 0xb8
	s_or_b32 s21, s4, 2
	s_mov_b64 s[18:19], 0
	s_branch .LBB0_1102

; DI ArgP getargs() { ArgP r; r.p = (const __attribute__((address_space(4))) Args*)__builtin_amdgcn_kernarg_segment_ptr(); asm volatile("" : "+s"(r.p)); return r; }
; #define WSB (getargs().ws())
;     DI bool next(int i, Unit& u) const {
;         const long L = (long)i * G + c; if (L >= nwg) return false;
;         int wgid = (int)L; { const int q = nwg / NXCD, r = nwg % NXCD, xcd = wgid % NXCD, off = wgid / NXCD; wgid = (xcd < r ? xcd * (q + 1) : r * (q + 1) + (xcd - r) * q) + off; }
;         const int nig = WGM * nN, gid = wgid / nig, fm = gid * WGM, gsz = (nM - fm) < WGM ? (nM - fm) : WGM;
;         u.pm = fm + ((wgid % nig) % gsz); u.pn = (wgid % nig) / gsz; return true;
; __global__ void __launch_bounds__(512, 2) fwd_kernel(Args a_unused) {
;     ...
;     { EpiUp E{(bf16_t*)(WSB + O_ACT), RSS + 1 * S, getargs().in(24), getargs().in(25), lds + 131072};
;       pg8::gemm_phase<true>(wv, lds, XBP, 1024, (const bf16_t*)(WSB + O_WUPT0), 1024, 1024, 67, 22, E); }
.LBB0_1102:
	s_mov_b64 s[4:5], s[100:101]
	s_mov_b64 s[6:7], s[100:101]
	s_load_dwordx2 s[8:9], s[16:17], 0xc8
	s_andn2_b64 vcc, exec, s[18:19]
	s_ashr_i32 s12, s24, 3
	s_cbranch_vccnz .LBB0_1104
	s_mul_i32 s21, s23, 0xb9

; #define LAS __attribute__((address_space(3)))
; DI int ltid(int wv) { asm volatile("" : "+s"(wv)); int l = __builtin_amdgcn_mbcnt_hi(~0u, __builtin_amdgcn_mbcnt_lo(~0u, 0u)); asm volatile("" : "+v"(l)); return wv * 64 + l; }
; DI unsigned xb_ld(unsigned* p) { return __hip_atomic_load(p, __ATOMIC_RELAXED, __HIP_MEMORY_SCOPE_AGENT); }
; DI unsigned xb_add(unsigned* p, unsigned v) { return __hip_atomic_fetch_add(p, v, __ATOMIC_RELAXED, __HIP_MEMORY_SCOPE_AGENT); }
; DI unsigned xb_xcc_id() { return (unsigned)__builtin_amdgcn_s_getreg((3 << 11) | 20) & 0xFu; }
; DI void xcd_barrier_complete(unsigned* bar, unsigned x, unsigned& nloc, unsigned& nx) {
;     const unsigned G = gridDim.x;
;     unsigned sum, cnt, mine, sp = 0u;
;     for (;;) {
;         sum = 0u; cnt = 0u; mine = 0u;
; #pragma unroll
;         for (unsigned j = 0; j < 16; ++j) { const unsigned c = xb_ld(&bar[XB_XCNT(j)]); sum += c; cnt += (c > 0u) ? 1u : 0u; mine = (j == x) ? c : mine; }
;         if (sum == G) break;
; DI void xcd_barrier(int wv, unsigned* bar, volatile LAS unsigned* st) {
;     asm volatile("s_waitcnt vmcnt(0)" ::: "memory");
;     __syncthreads();
;     if (ltid(wv) == 0) {
;         const unsigned x = xb_xcc_id();
;         __builtin_amdgcn_s_waitcnt(0);
;         unsigned nloc = st[0], nx = st[1];
;         if (nloc == 0u) { xcd_barrier_complete(bar, x, nloc, nx); st[0] = nloc; st[1] = nx; }
;         const unsigned old = xb_add(&bar[XB_XSUB(x)], 1u);
.LBB0_1126:
	s_mov_b64 s[2:3], s[82:83]
	s_mov_b32 s0, s50
	s_waitcnt vmcnt(0)
	s_waitcnt lgkmcnt(0)
	s_barrier
	s_lshl_b32 s0, s0, 6
	v_mov_b32_e32 v0, v192
	s_sub_i32 s0, 0, s0
	s_nop 0
	v_cmp_eq_u32_e32 vcc, s0, v0
	s_and_saveexec_b64 s[0:1], vcc
	s_xor_b64 s[0:1], exec, s[0:1]
	s_cbranch_execz .LBB0_1179
	s_add_i32 s5, 0, 0x22000
	v_mov_b32_e32 v0, s5
	s_mov_b64 s[2:3], s[100:101]
	s_getreg_b32 s4, hwreg(HW_REG_XCC_ID, 0, 4)
	s_waitcnt vmcnt(0) expcnt(0) lgkmcnt(0)
	ds_read_b32 v2, v0
	s_add_i32 s5, 0, 0x22004
	v_mov_b32_e32 v0, s5
	ds_read_b32 v0, v0
	s_and_b32 s33, s4, 15
	s_waitcnt lgkmcnt(1)
	v_cmp_ne_u32_e32 vcc, 0, v2
	s_cbranch_vccnz .LBB0_1142
	s_add_u32 s4, s2, 0x1d83200
	s_addc_u32 s5, s3, 0
	s_add_u32 s6, s2, 0x1d83400
	s_addc_u32 s7, s3, 0
	s_add_u32 s8, s2, 0x1d83500
	s_addc_u32 s9, s3, 0
	s_add_u32 s10, s2, 0x1d83600
	s_addc_u32 s11, s3, 0
	s_add_u32 s12, s2, 0x1d83700
	s_addc_u32 s13, s3, 0
	s_add_u32 s14, s2, 0x1d83800
	s_addc_u32 s15, s3, 0
	s_add_u32 s16, s2, 0x1d83900
	s_addc_u32 s17, s3, 0
	s_add_u32 s18, s2, 0x1d83a00
	s_addc_u32 s19, s3, 0
	s_add_u32 s20, s2, 0x1d83b00
	s_addc_u32 s21, s3, 0
	s_add_u32 s22, s2, 0x1d83c00
	s_addc_u32 s23, s3, 0
	s_add_u32 s24, s2, 0x1d83d00
	s_addc_u32 s25, s3, 0
	s_add_u32 s26, s2, 0x1d83e00
	s_addc_u32 s27, s3, 0
	s_add_u32 s28, s2, 0x1d83f00
	s_addc_u32 s29, s3, 0
	s_add_u32 s30, s2, 0x1d84000
	s_addc_u32 s31, s3, 0
	s_add_u32 s34, s2, 0x1d84100
	s_load_dword s46, s[88:89], 0x0
	s_addc_u32 s35, s3, 0
	s_add_u32 s36, s2, 0x1d84200
	s_addc_u32 s37, s3, 0
	s_add_u32 s38, s2, 0x1d84300
	s_addc_u32 s39, s3, 0
	s_mov_b32 s47, 1
	v_mov_b32_e32 v16, 0
	s_branch .LBB0_1130

; #define WSB (getargs().ws())
;     DI bool next(int i, Unit& u) const {
;         const long L = (long)i * G + c; if (L >= nwg) return false;
;         int wgid = (int)L; { const int q = nwg / NXCD, r = nwg % NXCD, xcd = wgid % NXCD, off = wgid / NXCD; wgid = (xcd < r ? xcd * (q + 1) : r * (q + 1) + (xcd - r) * q) + off; }
;         const int nig = WGM * nN, gid = wgid / nig, fm = gid * WGM, gsz = (nM - fm) < WGM ? (nM - fm) : WGM;
;         u.pm = fm + ((wgid % nig) % gsz); u.pn = (wgid % nig) / gsz; return true;
; __global__ void __launch_bounds__(512, 2) fwd_kernel(Args a_unused) {
;     ...
;     { EpiRes<true> E{nullptr, XBP, RSS + 2 * S, dry_};
;       pg8::gemm_phase<false>(wv, lds, (const bf16_t*)(WSB + O_ACT), 2816, (const bf16_t*)(WSB + O_WDNT0), 2816, 2816, 64, 4, E); }
.LBB0_1181:
	s_mov_b64 s[2:3], s[100:101]
	s_mov_b64 s[4:5], s[100:101]
	s_mov_b64 s[6:7], s[100:101]
	s_mov_b64 s[0:1], s[100:101]
	s_ashr_i32 s30, s28, 31
	s_cmpk_lt_i32 s28, 0x100
	s_cselect_b64 s[8:9], -1, 0
	s_cmpk_gt_i32 s28, 0xff
	s_cbranch_scc1 .LBB0_1187
	s_ashr_i32 s10, s28, 31
	s_lshr_b32 s10, s10, 29
	s_add_i32 s14, s28, s10
	s_and_b32 s10, s14, -8
	s_sub_i32 s12, s28, s10
	s_cmp_gt_i32 s12, -1
	s_cbranch_scc0 .LBB0_1184
	s_lshl_b32 s13, s12, 5
	s_ashr_i32 s10, s14, 3
	s_cbranch_execz .LBB0_1185
	s_branch .LBB0_1186

; #define WSB (getargs().ws())
;     DI bool next(int i, Unit& u) const {
;         const long L = (long)i * G + c; if (L >= nwg) return false;
;         int wgid = (int)L; { const int q = nwg / NXCD, r = nwg % NXCD, xcd = wgid % NXCD, off = wgid / NXCD; wgid = (xcd < r ? xcd * (q + 1) : r * (q + 1) + (xcd - r) * q) + off; }
;         const int nig = WGM * nN, gid = wgid / nig, fm = gid * WGM, gsz = (nM - fm) < WGM ? (nM - fm) : WGM;
;         u.pm = fm + ((wgid % nig) % gsz); u.pn = (wgid % nig) / gsz; return true;
; __global__ void __launch_bounds__(512, 2) fwd_kernel(Args a_unused) {
;     ...
;     { EpiQOK E{(bf16_t*)(WSB + O_QOK), RSS + 2 * S, (bf16_t*)(WSB + O_KVT)};
;       pg8::gemm_phase<false>(wv, lds, XBP, 1024, (const bf16_t*)(WSB + O_WOINT), 1024, 1024, 64, 8, E); }
.LBB0_1283:
	s_mov_b64 s[2:3], s[100:101]
	s_mov_b64 s[4:5], s[100:101]
	s_mov_b64 s[6:7], s[100:101]
	s_mov_b64 s[12:13], s[100:101]
	s_mov_b64 s[0:1], s[100:101]
	s_ashr_i32 s45, s33, 31
	s_cmpk_lt_i32 s33, 0x200
	s_cselect_b64 s[14:15], -1, 0
	s_cmpk_gt_i32 s33, 0x1ff
	s_cbranch_scc1 .LBB0_1289
	s_ashr_i32 s8, s33, 31
	s_lshr_b32 s8, s8, 29
	s_add_i32 s16, s33, s8
	s_and_b32 s8, s16, -8
	s_sub_i32 s10, s33, s8
	s_cmp_gt_i32 s10, -1
	s_cbranch_scc0 .LBB0_1286
	s_lshl_b32 s11, s10, 6
	s_ashr_i32 s8, s16, 3
	s_cbranch_execz .LBB0_1287
	s_branch .LBB0_1288

; #define WSB (getargs().ws())
;     DI bool next(int i, Unit& u) const {
;         const long L = (long)i * G + c; if (L >= nwg) return false;
;         int wgid = (int)L; { const int q = nwg / NXCD, r = nwg % NXCD, xcd = wgid % NXCD, off = wgid / NXCD; wgid = (xcd < r ? xcd * (q + 1) : r * (q + 1) + (xcd - r) * q) + off; }
;         const int nig = WGM * nN, gid = wgid / nig, fm = gid * WGM, gsz = (nM - fm) < WGM ? (nM - fm) : WGM;
;         u.pm = fm + ((wgid % nig) % gsz); u.pn = (wgid % nig) / gsz; return true;
; __global__ void __launch_bounds__(512, 2) fwd_kernel(Args a_unused) {
;     ...
;     { EpiColBf16<1> E{(bf16_t*)(WSB + O_KVT) + (size_t)512 * S, S, RSS + 2 * S};
;       pg8::gemm_phase<false>(wv, lds, (const bf16_t*)(WSB + O_WOINT) + (size_t)2048 * 1024, 1024, XBP, 1024, 1024, 4, 64, E); }
.LBB0_1345:
	s_ashr_i32 s29, s25, 31
	s_mov_b64 s[6:7], s[100:101]
	s_mov_b64 s[0:1], s[100:101]
	s_lshr_b32 s2, s29, 29
	s_add_i32 s17, s25, s2
	s_and_b32 s2, s17, -8
	s_sub_i32 s16, s25, s2
	s_cmp_gt_i32 s16, -1
	s_cbranch_scc0 .LBB0_1347
	s_lshl_b32 s18, s16, 5
	s_mov_b64 s[12:13], 0
	s_branch .LBB0_1348

;     DI bool next(int i, Unit& u) const {
;         const long L = (long)i * G + c; if (L >= nwg) return false;
;         int wgid = (int)L; { const int q = nwg / NXCD, r = nwg % NXCD, xcd = wgid % NXCD, off = wgid / NXCD; wgid = (xcd < r ? xcd * (q + 1) : r * (q + 1) + (xcd - r) * q) + off; }
;         const int nig = WGM * nN, gid = wgid / nig, fm = gid * WGM, gsz = (nM - fm) < WGM ? (nM - fm) : WGM;
;         u.pm = fm + ((wgid % nig) % gsz); u.pn = (wgid % nig) / gsz; return true;
.LBB0_1348:
	s_mov_b64 s[2:3], s[100:101]
	s_mov_b64 s[4:5], s[100:101]
	s_andn2_b64 vcc, exec, s[12:13]
	s_ashr_i32 s8, s17, 3
	s_cbranch_vccnz .LBB0_1350
	s_mul_i32 s18, s16, 33

; #define LAS __attribute__((address_space(3)))
; DI int ltid(int wv) { asm volatile("" : "+s"(wv)); int l = __builtin_amdgcn_mbcnt_hi(~0u, __builtin_amdgcn_mbcnt_lo(~0u, 0u)); asm volatile("" : "+v"(l)); return wv * 64 + l; }
; DI void phase_m_gates(int wv, const ArgP a, LAS unsigned char* lds) {
;     unsigned char* ws = a.ws(); const int tid = ltid(wv), wave = tid >> 6, lane = tid & 63;
;     const bf16_t* XBr = (const bf16_t*)(ws + O_XB) + 2 * 1024; const u64* rowss = (const u64*)(ws + O_ROWSS) + 2 * S;
;     const float* Wg = a.in(17); const float* gn = a.in(16);
;     LAS float* wgs = (LAS float*)lds;
;     LAS float* pre = (LAS float*)(lds + 32768);
;     float* GB = (float*)(ws + O_GB); float* GE = (float*)(ws + O_GE); float* GPM = (float*)(ws + O_GPM);
;     float* BL = (float*)(ws + O_BL); float* ML = (float*)(ws + O_ML);
;     for (int e = tid; e < 8192; e += 512) { const int k = e >> 3, j = e & 7; wgs[j * 1024 + k] = Wg[(size_t)k * 3080 + 3072 + j] * gn[k]; }
.LBB0_1370:
	s_mov_b64 s[0:1], s[82:83]
	s_mov_b64 s[2:3], s[100:101]
	s_mov_b32 s4, s50
	v_mov_b32_e32 v9, v192
	s_nop 0
	v_lshl_add_u32 v0, s4, 6, v9
	s_movk_i32 s4, 0x2000
	v_cmp_gt_i32_e32 vcc, s4, v0
	v_and_b32_e32 v8, 7, v9
	s_and_saveexec_b64 s[4:5], vcc
	s_cbranch_execz .LBB0_1382
	s_load_dwordx4 s[8:11], s[0:1], 0x80
	v_max_i32_e32 v1, 0x1e00, v0
	v_sub_u32_e32 v1, v1, v0
	s_movk_i32 s6, 0x1ff
	v_add_u32_e32 v2, 0x1ff, v1
	v_lshl_add_u32 v10, v8, 12, 0
	v_cmp_lt_u32_e32 vcc, s6, v2
	s_mov_b64 s[6:7], -1
	v_mov_b32_e32 v1, v0
	s_and_saveexec_b64 s[12:13], vcc
	s_cbranch_execz .LBB0_1379
	v_lshrrev_b32_e32 v11, 9, v2
	v_add_u32_e32 v1, 0x200, v0
	v_add_u32_e32 v12, -1, v11
	v_cmp_lt_u32_e32 vcc, 1, v12
	v_mov_b64_e32 v[2:3], v[0:1]
	s_and_saveexec_b64 s[14:15], vcc
	s_cbranch_execz .LBB0_1376
	v_lshrrev_b32_e32 v2, 1, v12
	v_add_u32_e32 v2, 1, v2
	v_and_b32_e32 v13, -2, v2
	s_mov_b64 s[16:17], 0
	s_movk_i32 s18, 0x3020
	s_waitcnt lgkmcnt(0)
	v_mov_b64_e32 v[4:5], s[10:11]
	v_lshlrev_b32_e32 v6, 2, v8
	v_mov_b32_e32 v7, 0
	s_movk_i32 s19, 0x3000
	v_mov_b64_e32 v[2:3], v[0:1]

; #define LAS __attribute__((address_space(3)))
; DI int ltid(int wv) { asm volatile("" : "+s"(wv)); int l = __builtin_amdgcn_mbcnt_hi(~0u, __builtin_amdgcn_mbcnt_lo(~0u, 0u)); asm volatile("" : "+v"(l)); return wv * 64 + l; }
; DI unsigned xb_ld(unsigned* p) { return __hip_atomic_load(p, __ATOMIC_RELAXED, __HIP_MEMORY_SCOPE_AGENT); }
; DI unsigned xb_add(unsigned* p, unsigned v) { return __hip_atomic_fetch_add(p, v, __ATOMIC_RELAXED, __HIP_MEMORY_SCOPE_AGENT); }
; DI unsigned xb_xcc_id() { return (unsigned)__builtin_amdgcn_s_getreg((3 << 11) | 20) & 0xFu; }
; DI void xcd_barrier_complete(unsigned* bar, unsigned x, unsigned& nloc, unsigned& nx) {
;     const unsigned G = gridDim.x;
;     unsigned sum, cnt, mine, sp = 0u;
;     for (;;) {
;         sum = 0u; cnt = 0u; mine = 0u;
; #pragma unroll
;         for (unsigned j = 0; j < 16; ++j) { const unsigned c = xb_ld(&bar[XB_XCNT(j)]); sum += c; cnt += (c > 0u) ? 1u : 0u; mine = (j == x) ? c : mine; }
;         if (sum == G) break;
; DI void xcd_barrier(int wv, unsigned* bar, volatile LAS unsigned* st) {
;     asm volatile("s_waitcnt vmcnt(0)" ::: "memory");
;     __syncthreads();
;     if (ltid(wv) == 0) {
;         const unsigned x = xb_xcc_id();
;         __builtin_amdgcn_s_waitcnt(0);
;         unsigned nloc = st[0], nx = st[1];
;         if (nloc == 0u) { xcd_barrier_complete(bar, x, nloc, nx); st[0] = nloc; st[1] = nx; }
;         const unsigned old = xb_add(&bar[XB_XSUB(x)], 1u);
.LBB0_1407:
	s_mov_b64 s[2:3], s[82:83]
	s_mov_b32 s0, s50
	s_waitcnt vmcnt(0)
	s_barrier
	s_lshl_b32 s0, s0, 6
	v_mov_b32_e32 v0, v192
	s_sub_i32 s0, 0, s0
	s_nop 0
	v_cmp_eq_u32_e32 vcc, s0, v0
	s_and_saveexec_b64 s[0:1], vcc
	s_xor_b64 s[0:1], exec, s[0:1]
	s_cbranch_execz .LBB0_1460
	s_add_i32 s5, 0, 0x22000
	v_mov_b32_e32 v0, s5
	s_mov_b64 s[2:3], s[100:101]
	s_getreg_b32 s4, hwreg(HW_REG_XCC_ID, 0, 4)
	s_waitcnt vmcnt(0) expcnt(0) lgkmcnt(0)
	ds_read_b32 v2, v0
	s_add_i32 s5, 0, 0x22004
	v_mov_b32_e32 v0, s5
	ds_read_b32 v0, v0
	s_and_b32 s33, s4, 15
	s_waitcnt lgkmcnt(1)
	v_cmp_ne_u32_e32 vcc, 0, v2
	s_cbranch_vccnz .LBB0_1423
	s_add_u32 s4, s2, 0x1d83200
	s_addc_u32 s5, s3, 0
	s_add_u32 s6, s2, 0x1d83400
	s_addc_u32 s7, s3, 0
	s_add_u32 s8, s2, 0x1d83500
	s_addc_u32 s9, s3, 0
	s_add_u32 s10, s2, 0x1d83600
	s_addc_u32 s11, s3, 0
	s_add_u32 s12, s2, 0x1d83700
	s_addc_u32 s13, s3, 0
	s_add_u32 s14, s2, 0x1d83800
	s_addc_u32 s15, s3, 0
	s_add_u32 s16, s2, 0x1d83900
	s_addc_u32 s17, s3, 0
	s_add_u32 s18, s2, 0x1d83a00
	s_addc_u32 s19, s3, 0
	s_add_u32 s20, s2, 0x1d83b00
	s_addc_u32 s21, s3, 0
	s_add_u32 s22, s2, 0x1d83c00
	s_addc_u32 s23, s3, 0
	s_add_u32 s24, s2, 0x1d83d00
	s_addc_u32 s25, s3, 0
	s_add_u32 s26, s2, 0x1d83e00
	s_addc_u32 s27, s3, 0
	s_add_u32 s28, s2, 0x1d83f00
	s_addc_u32 s29, s3, 0
	s_add_u32 s30, s2, 0x1d84000
	s_addc_u32 s31, s3, 0
	s_add_u32 s34, s2, 0x1d84100
	s_load_dword s46, s[88:89], 0x0
	s_addc_u32 s35, s3, 0
	s_add_u32 s36, s2, 0x1d84200
	s_addc_u32 s37, s3, 0
	s_add_u32 s38, s2, 0x1d84300
	s_addc_u32 s39, s3, 0
	s_mov_b32 s47, 1
	v_mov_b32_e32 v16, 0
	s_branch .LBB0_1411

; DI int ltid(int wv) { asm volatile("" : "+s"(wv)); int l = __builtin_amdgcn_mbcnt_hi(~0u, __builtin_amdgcn_mbcnt_lo(~0u, 0u)); asm volatile("" : "+v"(l)); return wv * 64 + l; }
; DI void phase_m_dc(int wv, const ArgP a) {
;     unsigned char* ws = a.ws(); const int tid = ltid(wv), lane = tid & 63, r32 = lane & 31, hi = lane >> 5; const int w = __builtin_amdgcn_readfirstlane(tid >> 6);
;     const float* __restrict__ BL = (const float*)(ws + O_BL); const float* __restrict__ ML = (const float*)(ws + O_ML); float* __restrict__ NST = (float*)(ws + O_NST);
;     const float* __restrict__ GE = (const float*)(ws + O_GE); const bf16_t* __restrict__ KVT = (const bf16_t*)(ws + O_KVT); bf16_t* __restrict__ CST = (bf16_t*)(ws + O_CST);
; #pragma unroll 2
;     for (int u = blockIdx.x; u < 1024; u += gridDim.x) {
;         const int c = u >> 2, h = u & 3; const size_t t0 = (size_t)c * 64;
;         const float emax = ML[c * 4 + h] - BL[c * 4 + h];
;         bf16x8 bfr[4];
;         { const bf16_t* vp = KVT + (size_t)(512 + h * 256 + 32 * w + r32) * S + t0 + 8 * hi; const float* gp = GE + (size_t)h * S + t0 + 8 * hi;
.LBB0_1460:
	s_or_b64 exec, exec, s[0:1]
	s_cmpk_lt_i32 s80, 0x400
	s_mov_b64 s[0:1], s[82:83]
	s_mov_b32 s2, s50
	s_waitcnt lgkmcnt(0)
	v_mov_b32_e32 v0, v192
	s_barrier
	s_cselect_b64 s[6:7], -1, 0
	s_and_b64 vcc, exec, s[6:7]
	v_lshl_add_u32 v30, s2, 6, v0
	s_nop 0
	v_readfirstlane_b32 s2, v30
	s_cbranch_vccz .LBB0_1465
	s_mov_b64 s[4:5], s[100:101]
	s_movk_i32 s3, 0xffe0
	v_and_b32_e32 v48, 31, v0
	s_load_dword s18, s[88:89], 0x0
	v_mov_b32_e32 v33, 0
	s_waitcnt lgkmcnt(0)
	s_add_u32 s12, s4, 0x1d00000
	s_addc_u32 s13, s5, 0
	s_add_u32 s14, s4, 0x1d01000
	s_addc_u32 s15, s5, 0
	s_add_u32 s16, s4, 0x1c80000
	s_addc_u32 s17, s5, 0
	s_add_u32 s0, s4, 0xbe0b000
	s_addc_u32 s1, s5, 0
	s_ashr_i32 s2, s2, 1
	v_mov_b32_e32 v1, s2
	s_and_b32 s8, s2, 0xffffffe0
	v_bfi_b32 v1, s3, v1, v0
	v_lshrrev_b32_e32 v0, 2, v0
	v_and_b32_e32 v0, 8, v0
	s_ashr_i32 s2, s8, 31
	v_or_b32_e32 v2, s8, v48
	v_mov_b32_e32 v3, s2
	v_lshlrev_b32_e32 v32, 1, v0
	s_movk_i32 s2, 0x80
	v_ashrrev_i32_e32 v31, 31, v30
	v_lshl_add_u64 v[4:5], s[4:5], 0, v[32:33]
	v_cmp_gt_i32_e32 vcc, s2, v30
	v_lshl_add_u64 v[6:7], v[30:31], 2, s[4:5]
	s_mov_b64 s[2:3], 0x1d03000
	v_lshlrev_b64 v[2:3], 8, v[2:3]
	v_lshl_add_u64 v[34:35], v[6:7], 0, s[2:3]
	v_lshl_add_u64 v[2:3], v[4:5], 0, v[2:3]
	s_mov_b64 s[2:3], 0x3e0b000
	v_add_u32_e32 v49, 0x200, v1
	v_lshl_add_u64 v[36:37], v[2:3], 0, s[2:3]
	v_lshlrev_b32_e32 v38, 1, v0
	v_mov_b32_e32 v39, v33
	v_lshlrev_b32_e32 v31, 2, v0
	s_mov_b32 s19, 0x100000
	s_mov_b32 s20, 0x200000
	s_mov_b32 s21, 0x300000
	s_mov_b32 s2, s80
	s_branch .LBB0_1463

; #define LAS __attribute__((address_space(3)))
; DI int ltid(int wv) { asm volatile("" : "+s"(wv)); int l = __builtin_amdgcn_mbcnt_hi(~0u, __builtin_amdgcn_mbcnt_lo(~0u, 0u)); asm volatile("" : "+v"(l)); return wv * 64 + l; }
; DI unsigned xb_ld(unsigned* p) { return __hip_atomic_load(p, __ATOMIC_RELAXED, __HIP_MEMORY_SCOPE_AGENT); }
; DI unsigned xb_add(unsigned* p, unsigned v) { return __hip_atomic_fetch_add(p, v, __ATOMIC_RELAXED, __HIP_MEMORY_SCOPE_AGENT); }
; DI unsigned xb_xcc_id() { return (unsigned)__builtin_amdgcn_s_getreg((3 << 11) | 20) & 0xFu; }
; DI void xcd_barrier_complete(unsigned* bar, unsigned x, unsigned& nloc, unsigned& nx) {
;     const unsigned G = gridDim.x;
;     unsigned sum, cnt, mine, sp = 0u;
;     for (;;) {
;         sum = 0u; cnt = 0u; mine = 0u;
; #pragma unroll
;         for (unsigned j = 0; j < 16; ++j) { const unsigned c = xb_ld(&bar[XB_XCNT(j)]); sum += c; cnt += (c > 0u) ? 1u : 0u; mine = (j == x) ? c : mine; }
;         if (sum == G) break;
; DI void xcd_barrier(int wv, unsigned* bar, volatile LAS unsigned* st) {
;     asm volatile("s_waitcnt vmcnt(0)" ::: "memory");
;     __syncthreads();
;     if (ltid(wv) == 0) {
;         const unsigned x = xb_xcc_id();
;         __builtin_amdgcn_s_waitcnt(0);
;         unsigned nloc = st[0], nx = st[1];
;         if (nloc == 0u) { xcd_barrier_complete(bar, x, nloc, nx); st[0] = nloc; st[1] = nx; }
;         const unsigned old = xb_add(&bar[XB_XSUB(x)], 1u);
.LBB0_1465:
	s_mov_b64 s[2:3], s[82:83]
	s_mov_b32 s0, s50
	s_waitcnt vmcnt(0)
	s_barrier
	s_lshl_b32 s0, s0, 6
	v_mov_b32_e32 v0, v192
	s_sub_i32 s0, 0, s0
	s_nop 0
	v_cmp_eq_u32_e32 vcc, s0, v0
	s_and_saveexec_b64 s[0:1], vcc
	s_xor_b64 s[0:1], exec, s[0:1]
	s_cbranch_execz .LBB0_1518
	s_add_i32 s5, 0, 0x22000
	v_mov_b32_e32 v0, s5
	s_mov_b64 s[2:3], s[100:101]
	s_getreg_b32 s4, hwreg(HW_REG_XCC_ID, 0, 4)
	s_waitcnt vmcnt(0) expcnt(0) lgkmcnt(0)
	ds_read_b32 v2, v0
	s_add_i32 s5, 0, 0x22004
	v_mov_b32_e32 v0, s5
	ds_read_b32 v0, v0
	s_and_b32 s33, s4, 15
	s_waitcnt lgkmcnt(1)
	v_cmp_ne_u32_e32 vcc, 0, v2
	s_cbranch_vccnz .LBB0_1481
	s_add_u32 s4, s2, 0x1d83200
	s_addc_u32 s5, s3, 0
	s_add_u32 s8, s2, 0x1d83400
	s_addc_u32 s9, s3, 0
	s_add_u32 s10, s2, 0x1d83500
	s_addc_u32 s11, s3, 0
	s_add_u32 s12, s2, 0x1d83600
	s_addc_u32 s13, s3, 0
	s_add_u32 s14, s2, 0x1d83700
	s_addc_u32 s15, s3, 0
	s_add_u32 s16, s2, 0x1d83800
	s_addc_u32 s17, s3, 0
	s_add_u32 s18, s2, 0x1d83900
	s_addc_u32 s19, s3, 0
	s_add_u32 s20, s2, 0x1d83a00
	s_addc_u32 s21, s3, 0
	s_add_u32 s22, s2, 0x1d83b00
	s_addc_u32 s23, s3, 0
	s_add_u32 s24, s2, 0x1d83c00
	s_addc_u32 s25, s3, 0
	s_add_u32 s26, s2, 0x1d83d00
	s_addc_u32 s27, s3, 0
	s_add_u32 s28, s2, 0x1d83e00
	s_addc_u32 s29, s3, 0
	s_add_u32 s30, s2, 0x1d83f00
	s_addc_u32 s31, s3, 0
	s_add_u32 s34, s2, 0x1d84000
	s_addc_u32 s35, s3, 0
	s_add_u32 s36, s2, 0x1d84100
	s_load_dword s48, s[88:89], 0x0
	s_addc_u32 s37, s3, 0
	s_add_u32 s38, s2, 0x1d84200
	s_addc_u32 s39, s3, 0
	s_add_u32 s40, s2, 0x1d84300
	s_addc_u32 s41, s3, 0
	s_mov_b32 s49, 1
	v_mov_b32_e32 v16, 0
	s_branch .LBB0_1469

; #define LAS __attribute__((address_space(3)))
; DI int ltid(int wv) { asm volatile("" : "+s"(wv)); int l = __builtin_amdgcn_mbcnt_hi(~0u, __builtin_amdgcn_mbcnt_lo(~0u, 0u)); asm volatile("" : "+v"(l)); return wv * 64 + l; }
; DI void phase_m_comb(int wv, const ArgP a, LAS unsigned char* lds, int dry) {
;     unsigned char* ws = a.ws(); const int tid = ltid(wv);
;     const float* BL = (const float*)(ws + O_BL); const float* ML = (const float*)(ws + O_ML); float* MST = (float*)(ws + O_MST); float* NST = (float*)(ws + O_NST);
;     bf16_t* CST = (bf16_t*)(ws + O_CST);
;     LAS float* bls = (LAS float*)lds; LAS float* mls = bls + 1024; LAS float* ga = mls + 1024; LAS float* gb = ga + 1024;
;     for (int e = tid; e < 1024; e += 512) { bls[e] = BL[e]; mls[e] = ML[e]; }
;     __syncthreads();
.LBB0_1518:
	s_or_b64 exec, exec, s[0:1]
	s_mov_b64 s[0:1], s[82:83]
	s_waitcnt lgkmcnt(0)
	s_barrier
	s_mov_b64 s[0:1], s[100:101]
	s_mov_b32 s14, s50
	v_mov_b32_e32 v4, v192
	s_lshl_b32 s16, s14, 6
	s_movk_i32 s2, 0x400
	v_add_u32_e32 v2, s16, v4
	v_cmp_gt_i32_e32 vcc, s2, v2
	s_and_saveexec_b64 s[2:3], vcc
	s_cbranch_execz .LBB0_1531
	v_max_i32_e32 v0, 0x200, v2
	v_sub_u32_e32 v0, v0, v2
	s_movk_i32 s4, 0x1ff
	v_add_u32_e32 v1, 0x1ff, v0
	v_cmp_lt_u32_e32 vcc, s4, v1
	s_mov_b64 s[8:9], -1
	v_mov_b32_e32 v0, v2
	s_and_saveexec_b64 s[4:5], vcc
	s_cbranch_execz .LBB0_1528
	v_lshrrev_b32_e32 v5, 9, v1
	s_waitcnt lgkmcnt(0)
	s_add_u32 s8, s0, 0x1d00000
	s_addc_u32 s9, s1, 0
	v_add_u32_e32 v0, -1, v5
	s_add_u32 s10, s0, 0x1d01000
	v_add_u32_e32 v3, 0x200, v2
	v_lshrrev_b32_e32 v1, 1, v0
	s_addc_u32 s11, s1, 0
	v_add_u32_e32 v6, 1, v1
	v_cmp_lt_u32_e32 vcc, 5, v0
	v_mov_b32_e32 v9, 0
	v_mov_b64_e32 v[0:1], v[2:3]
	s_and_saveexec_b64 s[12:13], vcc
	s_cbranch_execz .LBB0_1524
	s_lshl_b32 s14, s14, 8
	s_add_i32 s14, s14, 0
	v_and_b32_e32 v7, -4, v6
	s_mov_b32 s17, 0
	v_lshl_add_u32 v8, v4, 2, s14
	s_mov_b64 s[14:15], 0
	v_mov_b64_e32 v[0:1], v[2:3]

; #define LAS __attribute__((address_space(3)))
; DI int ltid(int wv) { asm volatile("" : "+s"(wv)); int l = __builtin_amdgcn_mbcnt_hi(~0u, __builtin_amdgcn_mbcnt_lo(~0u, 0u)); asm volatile("" : "+v"(l)); return wv * 64 + l; }
; DI unsigned xb_ld(unsigned* p) { return __hip_atomic_load(p, __ATOMIC_RELAXED, __HIP_MEMORY_SCOPE_AGENT); }
; DI unsigned xb_add(unsigned* p, unsigned v) { return __hip_atomic_fetch_add(p, v, __ATOMIC_RELAXED, __HIP_MEMORY_SCOPE_AGENT); }
; DI unsigned xb_xcc_id() { return (unsigned)__builtin_amdgcn_s_getreg((3 << 11) | 20) & 0xFu; }
; DI void xcd_barrier_complete(unsigned* bar, unsigned x, unsigned& nloc, unsigned& nx) {
;     const unsigned G = gridDim.x;
;     unsigned sum, cnt, mine, sp = 0u;
;     for (;;) {
;         sum = 0u; cnt = 0u; mine = 0u;
; #pragma unroll
;         for (unsigned j = 0; j < 16; ++j) { const unsigned c = xb_ld(&bar[XB_XCNT(j)]); sum += c; cnt += (c > 0u) ? 1u : 0u; mine = (j == x) ? c : mine; }
;         if (sum == G) break;
; DI void xcd_barrier(int wv, unsigned* bar, volatile LAS unsigned* st) {
;     asm volatile("s_waitcnt vmcnt(0)" ::: "memory");
;     __syncthreads();
;     if (ltid(wv) == 0) {
;         const unsigned x = xb_xcc_id();
;         __builtin_amdgcn_s_waitcnt(0);
;         unsigned nloc = st[0], nx = st[1];
;         if (nloc == 0u) { xcd_barrier_complete(bar, x, nloc, nx); st[0] = nloc; st[1] = nx; }
;         const unsigned old = xb_add(&bar[XB_XSUB(x)], 1u);
.LBB0_1550:
	s_mov_b64 s[2:3], s[82:83]
	s_mov_b32 s0, s50
	s_barrier
	s_waitcnt vmcnt(0)
	s_barrier
	s_lshl_b32 s0, s0, 6
	v_mov_b32_e32 v0, v192
	s_sub_i32 s0, 0, s0
	s_nop 0
	v_cmp_eq_u32_e32 vcc, s0, v0
	s_and_saveexec_b64 s[0:1], vcc
	s_xor_b64 s[0:1], exec, s[0:1]
	s_cbranch_execz .LBB0_1603
	s_add_i32 s5, 0, 0x22000
	v_mov_b32_e32 v0, s5
	s_mov_b64 s[2:3], s[100:101]
	s_getreg_b32 s4, hwreg(HW_REG_XCC_ID, 0, 4)
	s_waitcnt vmcnt(0) expcnt(0) lgkmcnt(0)
	ds_read_b32 v2, v0
	s_add_i32 s5, 0, 0x22004
	v_mov_b32_e32 v0, s5
	ds_read_b32 v0, v0
	s_and_b32 s33, s4, 15
	s_waitcnt lgkmcnt(1)
	v_cmp_ne_u32_e32 vcc, 0, v2
	s_cbranch_vccnz .LBB0_1566
	s_add_u32 s4, s2, 0x1d83200
	s_addc_u32 s5, s3, 0
	s_add_u32 s8, s2, 0x1d83400
	s_addc_u32 s9, s3, 0
	s_add_u32 s10, s2, 0x1d83500
	s_addc_u32 s11, s3, 0
	s_add_u32 s12, s2, 0x1d83600
	s_addc_u32 s13, s3, 0
	s_add_u32 s14, s2, 0x1d83700
	s_addc_u32 s15, s3, 0
	s_add_u32 s16, s2, 0x1d83800
	s_addc_u32 s17, s3, 0
	s_add_u32 s18, s2, 0x1d83900
	s_addc_u32 s19, s3, 0
	s_add_u32 s20, s2, 0x1d83a00
	s_addc_u32 s21, s3, 0
	s_add_u32 s22, s2, 0x1d83b00
	s_addc_u32 s23, s3, 0
	s_add_u32 s24, s2, 0x1d83c00
	s_addc_u32 s25, s3, 0
	s_add_u32 s26, s2, 0x1d83d00
	s_addc_u32 s27, s3, 0
	s_add_u32 s28, s2, 0x1d83e00
	s_addc_u32 s29, s3, 0
	s_add_u32 s30, s2, 0x1d83f00
	s_addc_u32 s31, s3, 0
	s_add_u32 s34, s2, 0x1d84000
	s_addc_u32 s35, s3, 0
	s_add_u32 s36, s2, 0x1d84100
	s_load_dword s48, s[88:89], 0x0
	s_addc_u32 s37, s3, 0
	s_add_u32 s38, s2, 0x1d84200
	s_addc_u32 s39, s3, 0
	s_add_u32 s40, s2, 0x1d84300
	s_addc_u32 s41, s3, 0
	s_mov_b32 s49, 1
	v_mov_b32_e32 v16, 0
	s_branch .LBB0_1554

; #define LAS __attribute__((address_space(3)))
; DI int ltid(int wv) { asm volatile("" : "+s"(wv)); int l = __builtin_amdgcn_mbcnt_hi(~0u, __builtin_amdgcn_mbcnt_lo(~0u, 0u)); asm volatile("" : "+v"(l)); return wv * 64 + l; }
; DI float fexp(float x) { return __builtin_amdgcn_exp2f(x * LOG2E); }
; DI void phase_m_out(int wv, const ArgP a, LAS unsigned char* lds, int dry) {
;     unsigned char* ws = a.ws(); const int tid = ltid(wv), lane = tid & 63, r32 = lane & 31, hi = lane >> 5; const int w = __builtin_amdgcn_readfirstlane(tid >> 6);
;     bf16_t* QOK = (bf16_t*)(ws + O_QOK); const bf16_t* KVT = (const bf16_t*)(ws + O_KVT); const bf16_t* CST = (const bf16_t*)(ws + O_CST);
;     const float* GB = (const float*)(ws + O_GB); const float* GE = (const float*)(ws + O_GE); const float* GPM = (const float*)(ws + O_GPM);
;     const float* MST = (const float*)(ws + O_MST); const float* NST = (const float*)(ws + O_NST); const float* ong = a.in(20);
;     LAS unsigned char* Qs = lds + MC_QS; LAS unsigned char* Ks = lds + MC_KS; LAS unsigned char* Sc = lds + MC_SC;
;     LAS float* F = (LAS float*)(lds + MC_F);
;     LAS float* f_b = F, *f_e = F + 64, *f_m = F + 128, *f_g = F + 192, *f_qn = F + 256, *f_ps = F + 320  , *f_n = F + 576  , *f_part = F + 704  ;
;     for (int u = blockIdx.x; u < 1024; u += gridDim.x) {
;         const int c = u >> 2, h = u & 3; const size_t t0 = (size_t)c * 64;
;         for (int e = tid; e < 1024; e += 512) { const int r = e >> 4, p = e & 15;
;             *(LAS u32x4*)(Qs + r * MC_QROW + p * 16) = *(const u32x4*)(QOK + (t0 + r) * 2048 + h * 128 + p * 8);
;             *(LAS u32x4*)(Ks + r * MC_QROW + p * 16) = *(const u32x4*)(QOK + (t0 + r) * 2048 + 1536 + h * 128 + p * 8); }
;         if (tid < 64) { const float mstv = MST[c * 4 + h]; const float b = GB[(size_t)h * S + t0 + tid], e = GE[(size_t)h * S + t0 + tid], pm = GPM[(size_t)h * S + t0 + tid];
;             const float m = b + fmaxf(mstv, pm); f_b[tid] = b; f_e[tid] = e; f_m[tid] = m; f_g[tid] = fexp(b + mstv - m); }
;         if (tid >= 64 && tid < 192) f_n[tid - 64] = NST[(size_t)(c * 4 + h) * 128 + tid - 64];
;         __syncthreads();
.LBB0_1603:
	s_or_b64 exec, exec, s[0:1]
	s_mov_b64 s[2:3], s[82:83]
	s_mov_b32 s0, s50
	s_waitcnt lgkmcnt(0)
	v_mov_b32_e32 v0, v192
	s_barrier
	s_and_b64 vcc, exec, s[6:7]
	v_lshl_add_u32 v32, s0, 6, v0
	s_nop 0
	v_readfirstlane_b32 s0, v32
	s_cbranch_vccz .LBB0_1654
	s_mov_b64 s[12:13], s[100:101]
	s_load_dwordx2 s[14:15], s[2:3], 0xa0
	v_subrev_u32_e32 v2, 64, v32
	s_movk_i32 s8, 0x80
	v_mov_b32_e32 v37, 0
	s_waitcnt lgkmcnt(0)
	s_add_u32 s2, s12, 0x7e0b000
	s_addc_u32 s3, s13, 0
	s_add_u32 s50, s12, 0xbe0b000
	s_addc_u32 s51, s13, 0
	s_add_u32 s52, s12, 0x1c40000
	s_addc_u32 s53, s13, 0
	s_add_u32 s54, s12, 0x1c80000
	s_addc_u32 s55, s13, 0
	s_add_u32 s56, s12, 0x1cc0000
	s_addc_u32 s57, s13, 0
	s_add_u32 s33, s12, 0x1d02000
	s_addc_u32 s63, s13, 0
	s_ashr_i32 s18, s0, 6
	v_mov_b32_e32 v36, v32
	s_cmp_gt_i32 s18, 3
	v_cmp_gt_u32_e64 s[8:9], s8, v2
	v_lshl_add_u64 v[2:3], v[36:37], 2, s[12:13]
	s_mov_b64 s[10:11], 0x1d02f00
	s_cselect_b64 s[58:59], -1, 0
	s_lshl_b32 s16, s18, 4
	v_lshl_add_u64 v[38:39], v[2:3], 0, s[10:11]
	s_sub_i32 s10, s16, 64
	v_bfe_u32 v2, v0, 2, 4
	v_or_b32_e32 v3, s10, v2
	v_or_b32_e32 v2, s16, v2
	s_and_b32 s19, s18, 1
	s_ashr_i32 s16, s0, 2
	v_and_b32_e32 v34, 31, v0
	v_lshl_add_u32 v47, v2, 2, 0
	s_movk_i32 s17, 0xffe0
	v_mov_b32_e32 v2, s16
	s_lshl_b32 s20, s19, 5
	s_movk_i32 s72, 0x110
	v_bfi_b32 v10, s17, v2, v0
	v_or_b32_e32 v2, s20, v34
	v_mad_u32_u24 v11, v2, s72, 0
	v_mul_lo_u32 v2, v10, s72
	v_bfe_u32 v4, v0, 5, 1
	v_lshl_add_u32 v43, v32, 2, 0
	v_add_u32_e32 v42, 0, v2
	s_movk_i32 s21, 0xfef4
	v_mad_u64_u32 v[44:45], s[16:17], v10, s21, v[42:43]
	v_lshlrev_b32_e32 v2, 2, v4
	v_and_b32_e32 v1, 63, v0
	v_and_b32_e32 v8, 3, v0
	v_or_b32_e32 v12, s20, v2
	s_movk_i32 s16, 0x8c
	v_lshlrev_b32_e32 v0, 4, v0
	v_mul_lo_u32 v5, v10, s16
	s_lshl_b32 s17, s19, 6
	v_and_b32_e32 v36, 0xf0, v0
	v_or_b32_e32 v0, 2, v12
	v_add3_u32 v45, v44, v5, s17
	s_lshl_b32 s17, s19, 9
	s_lshl_b32 s60, s18, 5
	v_mad_u32_u24 v59, v34, s72, 0
	v_cmp_le_i32_e64 s[18:19], v0, v10
	v_or_b32_e32 v0, 3, v12
	v_mad_i32_i24 v68, v34, s21, v59
	v_cmp_le_i32_e64 s[20:21], v0, v10
	v_or_b32_e32 v0, 8, v12
	v_cmp_le_i32_e64 s[22:23], v0, v10
	v_or_b32_e32 v0, 9, v12
	v_cmp_le_i32_e64 s[24:25], v0, v10
	v_or_b32_e32 v0, 10, v12
	v_cmp_le_i32_e64 s[26:27], v0, v10
	v_or_b32_e32 v0, 11, v12
	v_cmp_le_i32_e64 s[28:29], v0, v10
	v_or_b32_e32 v0, 16, v12
	v_cmp_le_i32_e64 s[30:31], v0, v10
	v_or_b32_e32 v0, 17, v12
	v_cmp_le_i32_e64 s[34:35], v0, v10
	v_or_b32_e32 v0, 18, v12
	v_cmp_le_i32_e64 s[36:37], v0, v10
	v_or_b32_e32 v0, 19, v12
	v_cmp_le_i32_e64 s[38:39], v0, v10
	v_or_b32_e32 v0, 24, v12
	v_cmp_le_i32_e64 s[40:41], v0, v10
	v_or_b32_e32 v0, 25, v12
	v_lshlrev_b32_e32 v40, 4, v4
	v_lshlrev_b32_e32 v46, 3, v4
	s_add_i32 s17, s17, 0
	v_lshlrev_b32_e32 v4, 8, v4
	v_lshlrev_b32_e32 v5, 2, v10
	s_ashr_i32 s61, s60, 31
	s_load_dword s73, s[88:89], 0x0
	v_cmp_le_i32_e64 s[42:43], v0, v10
	v_or_b32_e32 v0, 26, v12
	v_add3_u32 v49, s17, v4, v5
	v_or_b32_e32 v4, s60, v34
	v_mov_b32_e32 v5, s61
	v_mov_b32_e32 v41, v37
	v_mad_u32_u24 v13, v34, s16, v68
	s_and_b32 s0, s0, 0x3fffffc0
	s_lshl_b64 s[16:17], s[60:61], 2
	v_cmp_le_i32_e64 s[44:45], v0, v10
	v_or_b32_e32 v0, 27, v12
	v_lshl_add_u32 v35, v34, 2, 0
	v_mul_lo_u32 v3, v3, s72
	v_lshl_add_u64 v[6:7], s[12:13], 0, v[40:41]
	v_cmp_gt_u32_e64 s[12:13], 32, v1
	s_add_u32 s48, s14, s16
	v_cmp_le_i32_e64 s[46:47], v0, v10
	v_lshlrev_b64 v[0:1], 8, v[4:5]
	s_movk_i32 s4, 0x400
	v_add_u32_e32 v3, 0, v3
	v_lshlrev_b32_e32 v9, 7, v8
	v_cmp_eq_u32_e64 s[10:11], 0, v8
	v_lshl_add_u32 v14, s0, 2, v35
	s_addc_u32 s49, s15, s17
	v_lshlrev_b32_e32 v8, 6, v8
	v_lshl_add_u64 v[0:1], v[6:7], 0, v[0:1]
	s_mov_b64 s[64:65], 0x3e0b000
	s_mov_b32 s1, 0
	v_cmp_gt_i32_e64 s[4:5], s4, v32
	v_cmp_gt_i32_e64 s[6:7], 64, v32
	v_ashrrev_i32_e32 v33, 31, v32
	v_add_u32_e32 v69, 0x200, v4
	v_add_u32_e32 v48, 0, v36
	v_cmp_le_i32_e64 s[14:15], v12, v10
	v_lshl_add_u32 v70, v12, 2, 0
	v_cmp_lt_i32_e64 s[16:17], v12, v10
	v_lshl_add_u64 v[50:51], v[0:1], 0, s[64:65]
	v_lshl_add_u64 v[52:53], s[2:3], 0, v[36:37]
	v_lshl_add_u64 v[54:55], s[48:49], 0, v[40:41]
	s_movk_i32 s74, 0x1ff
	v_add_u32_e32 v41, v3, v8
	v_add_u32_e32 v71, 0, v9
	v_add_u32_e32 v72, v11, v40
	v_lshlrev_b32_e32 v36, 1, v46
	v_add_u32_e32 v73, v13, v40
	s_mov_b32 s62, 0x3b800000
	s_mov_b32 s75, 0x800000
	v_lshlrev_b32_e32 v56, 1, v2
	s_mov_b64 s[64:65], 0x20400
	v_add_u32_e32 v74, 0xb400, v14
	v_mov_b32_e32 v58, 0x358637bd
	s_mov_b32 s66, s80
	s_branch .LBB0_1606

; #define WSB (getargs().ws())
;     DI bool next(int i, Unit& u) const {
;         const long L = (long)i * G + c; if (L >= nwg) return false;
;         int wgid = (int)L; { const int q = nwg / NXCD, r = nwg % NXCD, xcd = wgid % NXCD, off = wgid / NXCD; wgid = (xcd < r ? xcd * (q + 1) : r * (q + 1) + (xcd - r) * q) + off; }
;         const int nig = WGM * nN, gid = wgid / nig, fm = gid * WGM, gsz = (nM - fm) < WGM ? (nM - fm) : WGM;
;         u.pm = fm + ((wgid % nig) % gsz); u.pn = (wgid % nig) / gsz; return true;
; __global__ void __launch_bounds__(512, 2) fwd_kernel(Args a_unused) {
;     ...
;     { EpiRes<true> E{nullptr, XBP, RSS + 3 * S, dry_};
;       pg8::gemm_phase<false>(wv, lds, (const bf16_t*)(WSB + O_QOK) + 512, 2048, (const bf16_t*)(WSB + O_WO2T), 1024, 1024, 64, 4, E); }
.LBB0_1709:
	s_mov_b64 s[2:3], s[100:101]
	s_mov_b64 s[4:5], s[100:101]
	s_mov_b64 s[6:7], s[100:101]
	s_mov_b64 s[0:1], s[100:101]
	s_ashr_i32 s37, s33, 31
	s_cmpk_lt_i32 s33, 0x100
	s_cselect_b64 s[8:9], -1, 0
	s_cmpk_gt_i32 s33, 0xff
	s_cbranch_scc1 .LBB0_1715
	s_ashr_i32 s10, s33, 31
	s_lshr_b32 s10, s10, 29
	s_add_i32 s14, s33, s10
	s_and_b32 s10, s14, -8
	s_sub_i32 s12, s33, s10
	s_cmp_gt_i32 s12, -1
	s_cbranch_scc0 .LBB0_1712
	s_lshl_b32 s13, s12, 5
	s_ashr_i32 s10, s14, 3
	s_cbranch_execz .LBB0_1713
	s_branch .LBB0_1714

; DI ArgP getargs() { ArgP r; r.p = (const __attribute__((address_space(4))) Args*)__builtin_amdgcn_kernarg_segment_ptr(); asm volatile("" : "+s"(r.p)); return r; }
; #define WSB (getargs().ws())
;     DI bool next(int i, Unit& u) const {
;         const long L = (long)i * G + c; if (L >= nwg) return false;
;         int wgid = (int)L; { const int q = nwg / NXCD, r = nwg % NXCD, xcd = wgid % NXCD, off = wgid / NXCD; wgid = (xcd < r ? xcd * (q + 1) : r * (q + 1) + (xcd - r) * q) + off; }
;         const int nig = WGM * nN, gid = wgid / nig, fm = gid * WGM, gsz = (nM - fm) < WGM ? (nM - fm) : WGM;
;         u.pm = fm + ((wgid % nig) % gsz); u.pn = (wgid % nig) / gsz; return true;
; __global__ void __launch_bounds__(512, 2) fwd_kernel(Args a_unused) {
;     ...
;     { EpiUp E{(bf16_t*)(WSB + O_ACT), RSS + 3 * S, getargs().in(24) + 3 * 5632, getargs().in(25) + 5632, lds + 131072};
;       pg8::gemm_phase<true>(wv, lds, XBP, 1024, (const bf16_t*)(WSB + O_WUPT1), 1024, 1024, 67, 22, E); }
.LBB0_1808:
	s_ashr_i32 s35, s33, 31
	s_mov_b64 s[10:11], s[100:101]
	s_mov_b64 s[0:1], s[100:101]
	s_lshr_b32 s4, s35, 29
	s_add_i32 s23, s33, s4
	s_and_b32 s4, s23, -8
	s_sub_i32 s21, s33, s4
	s_cmp_gt_i32 s21, 1
	s_cbranch_scc0 .LBB0_1810
	s_mul_i32 s4, s21, 0xb8
	s_or_b32 s20, s4, 2
	s_mov_b64 s[18:19], 0
	s_branch .LBB0_1811

; DI ArgP getargs() { ArgP r; r.p = (const __attribute__((address_space(4))) Args*)__builtin_amdgcn_kernarg_segment_ptr(); asm volatile("" : "+s"(r.p)); return r; }
; #define WSB (getargs().ws())
;     DI bool next(int i, Unit& u) const {
;         const long L = (long)i * G + c; if (L >= nwg) return false;
;         int wgid = (int)L; { const int q = nwg / NXCD, r = nwg % NXCD, xcd = wgid % NXCD, off = wgid / NXCD; wgid = (xcd < r ? xcd * (q + 1) : r * (q + 1) + (xcd - r) * q) + off; }
;         const int nig = WGM * nN, gid = wgid / nig, fm = gid * WGM, gsz = (nM - fm) < WGM ? (nM - fm) : WGM;
;         u.pm = fm + ((wgid % nig) % gsz); u.pn = (wgid % nig) / gsz; return true;
; __global__ void __launch_bounds__(512, 2) fwd_kernel(Args a_unused) {
;     ...
;     { EpiUp E{(bf16_t*)(WSB + O_ACT), RSS + 3 * S, getargs().in(24) + 3 * 5632, getargs().in(25) + 5632, lds + 131072};
;       pg8::gemm_phase<true>(wv, lds, XBP, 1024, (const bf16_t*)(WSB + O_WUPT1), 1024, 1024, 67, 22, E); }
.LBB0_1811:
	s_mov_b64 s[8:9], s[100:101]
	s_mov_b64 s[6:7], s[100:101]
	s_load_dwordx2 s[4:5], s[16:17], 0xc8
	s_andn2_b64 vcc, exec, s[18:19]
	s_ashr_i32 s12, s23, 3
	s_cbranch_vccnz .LBB0_1813
	s_mul_i32 s20, s21, 0xb9

; DI int ltid(int wv) { asm volatile("" : "+s"(wv)); int l = __builtin_amdgcn_mbcnt_hi(~0u, __builtin_amdgcn_mbcnt_lo(~0u, 0u)); asm volatile("" : "+v"(l)); return wv * 64 + l; }
; DI float rs_from_ss(u64 ssq) { return rsqrtf((float)ssq * (1.f / (1048576.f * 1024.f)) + EPS); }
; DI void phase_final(int wv, const ArgP a) {
;     float* out = a.out(); const u64* rowss = (const u64*)(a.ws() + O_ROWSS) + 4 * S; const float* g = a.in(27); const bf16_t* XBr = (const bf16_t*)(a.ws() + O_XB) + 2 * 1024;
;     for (size_t e = (size_t)blockIdx.x * 512 + ltid(wv); e < (size_t)S * 128; e += (size_t)gridDim.x * 512) { const int t = (int)(e >> 7), c = (int)(e & 127) * 8;
;         const float rs = rs_from_ss(rowss[t]); const u32x4 hb = __builtin_nontemporal_load((const u32x4*)(XBr + (size_t)t * 1024 + c)); const f32x4 g0 = *(const f32x4*)(g + c), g1 = *(const f32x4*)(g + c + 4);
.LBB0_1990:
	s_or_b64 exec, exec, s[0:1]
	s_waitcnt lgkmcnt(0)
	s_barrier
	s_mov_b32 s81, 0
	s_lshl_b64 s[0:1], s[80:81], 9
	v_lshl_add_u32 v2, s50, 6, v192
	v_ashrrev_i32_e32 v3, 31, v2
	v_lshl_add_u64 v[0:1], s[0:1], 0, v[2:3]
	s_mov_b64 s[0:1], 0x200000
	v_cmp_gt_u64_e32 vcc, s[0:1], v[0:1]
	s_and_saveexec_b64 s[0:1], vcc
	s_cbranch_execz .LBB0_1993
	s_mov_b64 s[2:3], s[100:101]
	s_load_dwordx4 s[4:7], s[82:83], 0xd8
	s_load_dword s10, s[88:89], 0x0
	s_mov_b32 s11, s81
	v_mov_b32_e32 v6, 0x358637bd
	s_waitcnt lgkmcnt(0)
	s_add_u32 s0, s2, 0x1900000
	s_addc_u32 s1, s3, 0
	s_add_u32 s2, s2, 0x1d88000
	s_addc_u32 s3, s3, 0
	s_lshl_b64 s[12:13], s[80:81], 12
	s_lshl_b64 s[8:9], s[10:11], 9
	v_lshl_add_u64 v[2:3], v[2:3], 3, s[12:13]
	s_lshl_b64 s[10:11], s[10:11], 12
	s_mov_b64 s[12:13], 0
	s_mov_b32 s16, 0x800000
	v_mov_b32_e32 v5, 0
	s_mov_b64 s[14:15], 0x1fffff

; __global__ void __launch_bounds__(512, 2) fwd_kernel(Args a_unused) {
	.amdhsa_kernel _Z10fwd_kernel4Args
		.amdhsa_group_segment_fixed_size 0
		.amdhsa_private_segment_fixed_size 0
		.amdhsa_kernarg_size 504
		.amdhsa_user_sgpr_count 2
		.amdhsa_user_sgpr_dispatch_ptr 0
		.amdhsa_user_sgpr_queue_ptr 0
		.amdhsa_user_sgpr_kernarg_segment_ptr 1
		.amdhsa_user_sgpr_dispatch_id 0
		.amdhsa_user_sgpr_kernarg_preload_length 0
		.amdhsa_user_sgpr_kernarg_preload_offset 0
		.amdhsa_user_sgpr_private_segment_size 0
		.amdhsa_uses_dynamic_stack 0
		.amdhsa_enable_private_segment 0
		.amdhsa_system_sgpr_workgroup_id_x 1
		.amdhsa_system_sgpr_workgroup_id_y 0
		.amdhsa_system_sgpr_workgroup_id_z 0
		.amdhsa_system_sgpr_workgroup_info 0
		.amdhsa_system_vgpr_workitem_id 2
		.amdhsa_next_free_vgpr 256
		.amdhsa_next_free_sgpr 102
		.amdhsa_accum_offset 256
		.amdhsa_reserve_vcc 1
		.amdhsa_float_round_mode_32 0
		.amdhsa_float_round_mode_16_64 0
		.amdhsa_float_denorm_mode_32 3
		.amdhsa_float_denorm_mode_16_64 3
		.amdhsa_dx10_clamp 1
		.amdhsa_ieee_mode 1
		.amdhsa_fp16_overflow 0
		.amdhsa_tg_split 0
		.amdhsa_exception_fp_ieee_invalid_op 0
		.amdhsa_exception_fp_denorm_src 0
		.amdhsa_exception_fp_ieee_div_zero 0
		.amdhsa_exception_fp_ieee_overflow 0
		.amdhsa_exception_fp_ieee_underflow 0
		.amdhsa_exception_fp_ieee_inexact 0
		.amdhsa_exception_int_div_zero 0
	.end_amdhsa_kernel

; __global__ void __launch_bounds__(512, 2) fwd_kernel(Args a_unused) {
amdhsa.kernels:
  - .agpr_count:     0
    .args:
      - .offset:         0
        .size:           248
        .value_kind:     by_value
      - .offset:         248
        .size:           4
        .value_kind:     hidden_block_count_x
      - .offset:         252
        .size:           4
        .value_kind:     hidden_block_count_y
      - .offset:         256
        .size:           4
        .value_kind:     hidden_block_count_z
      - .offset:         260
        .size:           2
        .value_kind:     hidden_group_size_x
      - .offset:         262
        .size:           2
        .value_kind:     hidden_group_size_y
      - .offset:         264
        .size:           2
        .value_kind:     hidden_group_size_z
      - .offset:         266
        .size:           2
        .value_kind:     hidden_remainder_x
      - .offset:         268
        .size:           2
        .value_kind:     hidden_remainder_y
      - .offset:         270
        .size:           2
        .value_kind:     hidden_remainder_z
      - .offset:         288
        .size:           8
        .value_kind:     hidden_global_offset_x
      - .offset:         296
        .size:           8
        .value_kind:     hidden_global_offset_y
      - .offset:         304
        .size:           8
        .value_kind:     hidden_global_offset_z
      - .offset:         312
        .size:           2
        .value_kind:     hidden_grid_dims
      - .offset:         336
        .size:           8
        .value_kind:     hidden_multigrid_sync_arg
      - .offset:         368
        .size:           4
        .value_kind:     hidden_dynamic_lds_size
    .group_segment_fixed_size: 0
    .kernarg_segment_align: 8
    .kernarg_segment_size: 504
    .language:       OpenCL C
    .language_version:
      - 2
      - 0
    .max_flat_workgroup_size: 512
    .name:           _Z10fwd_kernel4Args
    .private_segment_fixed_size: 0
    .sgpr_count:     108
    .sgpr_spill_count: 24
    .symbol:         _Z10fwd_kernel4Args.kd
    .uniform_work_group_size: 1
    .uses_dynamic_stack: false
    .vgpr_count:     256
    .vgpr_spill_count: 0
    .wavefront_size: 64
